# EpiLru: xconv row loads and n=1 gate params issued with the n=0 params ahead of the first wait (3 exposed round trips per tile -> 1)
# speedup vs baseline: 1.0071x; 1.0071x over previous
.LBB0_1205:
	s_ashr_i32 s21, s20, 31
	s_lshl_b64 s[26:27], s[20:21], 17
	s_add_u32 s26, s36, s26
	s_addc_u32 s27, s37, s27
	s_and_b64 s[6:7], s[6:7], exec
	s_cselect_b32 s7, s27, s31
	s_cselect_b32 s6, s26, s30
	s_add_i32 s23, 0, 0x10000
	v_add_u32_e32 v173, s23, v1
	ds_read_b128 v[2:5], v173
	ds_read_b128 v[6:9], v173 offset:1024
	ds_read_b128 v[10:13], v173 offset:2048
	ds_read_b128 v[14:17], v173 offset:3072
	s_add_u32 s46, s28, 0x40080
	s_addc_u32 s47, s29, 0
	s_add_i32 s50, s3, 0xc000
	v_lshl_add_u64 v[50:51], s[46:47], 0, v[138:139]
	s_mov_b32 m0, s50
	s_add_i32 s21, s3, 0xe000
	ds_read_b128 v[18:21], v172
	ds_read_b128 v[22:25], v172 offset:1024
	ds_read_b128 v[26:29], v172 offset:2048
	ds_read_b128 v[30:33], v172 offset:3072
	ds_read_b128 v[34:37], v172 offset:4096
	ds_read_b128 v[38:41], v172 offset:5120
	ds_read_b128 v[42:45], v172 offset:6144
	ds_read_b128 v[46:49], v172 offset:7168
	global_load_lds_dwordx4 v[50:51], off
	v_lshl_add_u64 v[50:51], s[46:47], 0, v[142:143]
	s_mov_b32 m0, s21
	s_nop 0
	global_load_lds_dwordx4 v[50:51], off
	s_waitcnt lgkmcnt(8)
	s_barrier
	s_waitcnt lgkmcnt(0)
	s_waitcnt lgkmcnt(0)
	v_mfma_f32_16x16x32_bf16 v[50:53], v[2:5], v[18:21], 0
	v_mfma_f32_16x16x32_bf16 v[54:57], v[10:13], v[18:21], 0
	v_mfma_f32_16x16x32_bf16 v[58:61], v[2:5], v[26:29], 0
	v_mfma_f32_16x16x32_bf16 v[62:65], v[10:13], v[26:29], 0
	v_mfma_f32_16x16x32_bf16 v[66:69], v[2:5], v[34:37], 0
	v_mfma_f32_16x16x32_bf16 v[70:73], v[10:13], v[34:37], 0
	v_mfma_f32_16x16x32_bf16 v[74:77], v[2:5], v[42:45], 0
	v_mfma_f32_16x16x32_bf16 v[78:81], v[10:13], v[42:45], 0
	v_mfma_f32_16x16x32_bf16 v[50:53], v[6:9], v[22:25], v[50:53]
	v_mfma_f32_16x16x32_bf16 v[54:57], v[14:17], v[22:25], v[54:57]
	v_mfma_f32_16x16x32_bf16 v[58:61], v[6:9], v[30:33], v[58:61]
	v_mfma_f32_16x16x32_bf16 v[62:65], v[14:17], v[30:33], v[62:65]
	v_mfma_f32_16x16x32_bf16 v[66:69], v[6:9], v[38:41], v[66:69]
	v_mfma_f32_16x16x32_bf16 v[70:73], v[14:17], v[38:41], v[70:73]
	v_mfma_f32_16x16x32_bf16 v[74:77], v[6:9], v[46:49], v[74:77]
	v_mfma_f32_16x16x32_bf16 v[78:81], v[14:17], v[46:49], v[78:81]
	s_barrier
	s_add_i32 s48, 0, 0x14000
	v_lshl_add_u64 v[170:171], s[30:31], 0, v[140:141]
	s_mov_b64 s[52:53], 0x100
	s_add_i32 s47, s23, s38
	v_add_u32_e32 v220, s48, v1
	v_lshl_add_u64 v[98:99], v[170:171], 0, s[52:53]
	s_mov_b32 m0, s47
	v_lshl_add_u64 v[186:187], s[30:31], 0, v[144:145]
	s_add_i32 s23, s47, 0x2000
	ds_read_b128 v[82:85], v220
	ds_read_b128 v[86:89], v220 offset:1024
	ds_read_b128 v[90:93], v220 offset:2048
	ds_read_b128 v[94:97], v220 offset:3072
	global_load_lds_dwordx4 v[98:99], off
	v_lshl_add_u64 v[98:99], v[186:187], 0, s[52:53]
	s_mov_b32 m0, s23
	s_nop 0
	global_load_lds_dwordx4 v[98:99], off
	s_barrier
	s_waitcnt lgkmcnt(0)
	s_waitcnt lgkmcnt(0)
	v_mfma_f32_16x16x32_bf16 v[98:101], v[82:85], v[18:21], 0
	v_mfma_f32_16x16x32_bf16 v[18:21], v[90:93], v[18:21], 0
	v_mfma_f32_16x16x32_bf16 v[98:101], v[86:89], v[22:25], v[98:101]
	v_mfma_f32_16x16x32_bf16 v[18:21], v[94:97], v[22:25], v[18:21]
	v_mfma_f32_16x16x32_bf16 v[22:25], v[82:85], v[26:29], 0
	v_mfma_f32_16x16x32_bf16 v[26:29], v[90:93], v[26:29], 0
	v_mfma_f32_16x16x32_bf16 v[22:25], v[86:89], v[30:33], v[22:25]
	v_mfma_f32_16x16x32_bf16 v[26:29], v[94:97], v[30:33], v[26:29]
	v_mfma_f32_16x16x32_bf16 v[30:33], v[82:85], v[34:37], 0
	v_mfma_f32_16x16x32_bf16 v[34:37], v[90:93], v[34:37], 0
	v_mfma_f32_16x16x32_bf16 v[30:33], v[86:89], v[38:41], v[30:33]
	v_mfma_f32_16x16x32_bf16 v[34:37], v[94:97], v[38:41], v[34:37]
	v_mfma_f32_16x16x32_bf16 v[38:41], v[82:85], v[42:45], 0
	v_mfma_f32_16x16x32_bf16 v[42:45], v[90:93], v[42:45], 0
	v_mfma_f32_16x16x32_bf16 v[38:41], v[86:89], v[46:49], v[38:41]
	v_mfma_f32_16x16x32_bf16 v[42:45], v[94:97], v[46:49], v[42:45]
	v_lshl_add_u64 v[188:189], s[28:29], 0, v[138:139]
	s_mov_b32 m0, s3
	v_lshl_add_u64 v[130:131], v[188:189], 0, s[52:53]
	v_lshl_add_u64 v[218:219], s[28:29], 0, v[142:143]
	s_barrier
	ds_read_b128 v[46:49], v172 offset:16384
	ds_read_b128 v[102:105], v172 offset:17408
	ds_read_b128 v[106:109], v172 offset:18432
	ds_read_b128 v[110:113], v172 offset:19456
	ds_read_b128 v[114:117], v172 offset:20480
	ds_read_b128 v[118:121], v172 offset:21504
	ds_read_b128 v[122:125], v172 offset:22528
	ds_read_b128 v[126:129], v172 offset:23552
	global_load_lds_dwordx4 v[130:131], off
	v_lshl_add_u64 v[130:131], v[218:219], 0, s[52:53]
	s_mov_b32 m0, s39
	s_nop 0
	global_load_lds_dwordx4 v[130:131], off
	s_barrier
	s_waitcnt lgkmcnt(0)
	s_waitcnt lgkmcnt(0)
	v_mfma_f32_16x16x32_bf16 v[130:133], v[2:5], v[46:49], 0
	v_mfma_f32_16x16x32_bf16 v[146:149], v[2:5], v[106:109], 0
	v_mfma_f32_16x16x32_bf16 v[154:157], v[2:5], v[114:117], 0
	v_mfma_f32_16x16x32_bf16 v[2:5], v[2:5], v[122:125], 0
	v_mfma_f32_16x16x32_bf16 v[130:133], v[6:9], v[102:105], v[130:133]
	v_mfma_f32_16x16x32_bf16 v[134:137], v[10:13], v[46:49], 0
	v_mfma_f32_16x16x32_bf16 v[146:149], v[6:9], v[110:113], v[146:149]
	v_mfma_f32_16x16x32_bf16 v[150:153], v[10:13], v[106:109], 0
	v_mfma_f32_16x16x32_bf16 v[154:157], v[6:9], v[118:121], v[154:157]
	v_mfma_f32_16x16x32_bf16 v[158:161], v[10:13], v[114:117], 0
	v_mfma_f32_16x16x32_bf16 v[2:5], v[6:9], v[126:129], v[2:5]
	v_mfma_f32_16x16x32_bf16 v[6:9], v[10:13], v[122:125], 0
	v_mfma_f32_16x16x32_bf16 v[134:137], v[14:17], v[102:105], v[134:137]
	v_mfma_f32_16x16x32_bf16 v[150:153], v[14:17], v[110:113], v[150:153]
	v_mfma_f32_16x16x32_bf16 v[158:161], v[14:17], v[118:121], v[158:161]
	v_mfma_f32_16x16x32_bf16 v[6:9], v[14:17], v[126:129], v[6:9]
	s_barrier
	s_add_u32 s52, s30, 0x10100
	s_addc_u32 s53, s31, 0
	s_add_i32 s48, s48, s38
	v_lshl_add_u64 v[10:11], s[52:53], 0, v[140:141]
	s_mov_b32 m0, s48
	s_add_i32 s46, s48, 0x2000
	global_load_lds_dwordx4 v[10:11], off
	v_lshl_add_u64 v[10:11], s[52:53], 0, v[144:145]
	s_mov_b32 m0, s46
	s_nop 0
	global_load_lds_dwordx4 v[10:11], off
	s_waitcnt vmcnt(6)
	s_barrier
	v_mfma_f32_16x16x32_bf16 v[10:13], v[82:85], v[46:49], 0
	v_mfma_f32_16x16x32_bf16 v[14:17], v[90:93], v[46:49], 0
	v_mfma_f32_16x16x32_bf16 v[10:13], v[86:89], v[102:105], v[10:13]
	v_mfma_f32_16x16x32_bf16 v[14:17], v[94:97], v[102:105], v[14:17]
	v_mfma_f32_16x16x32_bf16 v[46:49], v[82:85], v[106:109], 0
	v_mfma_f32_16x16x32_bf16 v[102:105], v[90:93], v[106:109], 0
	v_mfma_f32_16x16x32_bf16 v[106:109], v[82:85], v[114:117], 0
	v_mfma_f32_16x16x32_bf16 v[82:85], v[82:85], v[122:125], 0
	v_mfma_f32_16x16x32_bf16 v[46:49], v[86:89], v[110:113], v[46:49]
	v_mfma_f32_16x16x32_bf16 v[102:105], v[94:97], v[110:113], v[102:105]
	v_mfma_f32_16x16x32_bf16 v[106:109], v[86:89], v[118:121], v[106:109]
	v_mfma_f32_16x16x32_bf16 v[110:113], v[90:93], v[114:117], 0
	v_mfma_f32_16x16x32_bf16 v[82:85], v[86:89], v[126:129], v[82:85]
	v_mfma_f32_16x16x32_bf16 v[86:89], v[90:93], v[122:125], 0
	v_mfma_f32_16x16x32_bf16 v[110:113], v[94:97], v[118:121], v[110:113]
	v_mfma_f32_16x16x32_bf16 v[86:89], v[94:97], v[126:129], v[86:89]
	s_add_i32 s51, 0, 0x18000
	v_add_u32_e32 v232, s51, v1
	s_barrier
	ds_read_b128 v[90:93], v232
	ds_read_b128 v[94:97], v232 offset:1024
	ds_read_b128 v[114:117], v232 offset:2048
	ds_read_b128 v[118:121], v232 offset:3072
	s_add_u32 s52, s28, 0x40100
	s_addc_u32 s53, s29, 0
	s_mov_b32 m0, s40
	v_lshl_add_u64 v[202:203], s[52:53], 0, v[138:139]
	ds_read_b128 v[122:125], v172 offset:32768
	ds_read_b128 v[126:129], v172 offset:33792
	ds_read_b128 v[162:165], v172 offset:34816
	ds_read_b128 v[166:169], v172 offset:35840
	ds_read_b128 v[174:177], v172 offset:36864
	ds_read_b128 v[190:193], v172 offset:37888
	ds_read_b128 v[194:197], v172 offset:38912
	ds_read_b128 v[198:201], v172 offset:39936
	global_load_lds_dwordx4 v[202:203], off
	v_lshl_add_u64 v[202:203], s[52:53], 0, v[142:143]
	s_mov_b32 m0, s41
	s_nop 0
	global_load_lds_dwordx4 v[202:203], off
	s_waitcnt lgkmcnt(8)
	s_barrier
	s_waitcnt lgkmcnt(0)
	s_waitcnt lgkmcnt(0)
	v_mfma_f32_16x16x32_bf16 v[50:53], v[90:93], v[122:125], v[50:53]
	v_mfma_f32_16x16x32_bf16 v[54:57], v[114:117], v[122:125], v[54:57]
	v_mfma_f32_16x16x32_bf16 v[58:61], v[90:93], v[162:165], v[58:61]
	v_mfma_f32_16x16x32_bf16 v[62:65], v[114:117], v[162:165], v[62:65]
	v_mfma_f32_16x16x32_bf16 v[66:69], v[90:93], v[174:177], v[66:69]
	v_mfma_f32_16x16x32_bf16 v[70:73], v[114:117], v[174:177], v[70:73]
	v_mfma_f32_16x16x32_bf16 v[74:77], v[90:93], v[194:197], v[74:77]
	v_mfma_f32_16x16x32_bf16 v[78:81], v[114:117], v[194:197], v[78:81]
	v_mfma_f32_16x16x32_bf16 v[50:53], v[94:97], v[126:129], v[50:53]
	v_mfma_f32_16x16x32_bf16 v[54:57], v[118:121], v[126:129], v[54:57]
	v_mfma_f32_16x16x32_bf16 v[58:61], v[94:97], v[166:169], v[58:61]
	v_mfma_f32_16x16x32_bf16 v[62:65], v[118:121], v[166:169], v[62:65]
	v_mfma_f32_16x16x32_bf16 v[66:69], v[94:97], v[190:193], v[66:69]
	v_mfma_f32_16x16x32_bf16 v[70:73], v[118:121], v[190:193], v[70:73]
	v_mfma_f32_16x16x32_bf16 v[74:77], v[94:97], v[198:201], v[74:77]
	v_mfma_f32_16x16x32_bf16 v[78:81], v[118:121], v[198:201], v[78:81]
	s_barrier
	s_add_i32 s54, 0, 0x1c000
	s_mov_b64 s[52:53], 0x180
	s_add_i32 s51, s51, s38
	v_add_u32_e32 v233, s54, v1
	v_lshl_add_u64 v[170:171], v[170:171], 0, s[52:53]
	s_mov_b32 m0, s51
	s_add_i32 s49, s51, 0x2000
	ds_read_b128 v[202:205], v233
	ds_read_b128 v[206:209], v233 offset:1024
	ds_read_b128 v[210:213], v233 offset:2048
	ds_read_b128 v[214:217], v233 offset:3072
	global_load_lds_dwordx4 v[170:171], off
	v_lshl_add_u64 v[170:171], v[186:187], 0, s[52:53]
	s_mov_b32 m0, s49
	s_nop 0
	global_load_lds_dwordx4 v[170:171], off
	s_barrier
	s_waitcnt lgkmcnt(0)
	s_waitcnt lgkmcnt(0)
	v_mfma_f32_16x16x32_bf16 v[98:101], v[202:205], v[122:125], v[98:101]
	v_mfma_f32_16x16x32_bf16 v[18:21], v[210:213], v[122:125], v[18:21]
	v_mfma_f32_16x16x32_bf16 v[22:25], v[202:205], v[162:165], v[22:25]
	v_mfma_f32_16x16x32_bf16 v[26:29], v[210:213], v[162:165], v[26:29]
	v_mfma_f32_16x16x32_bf16 v[30:33], v[202:205], v[174:177], v[30:33]
	v_mfma_f32_16x16x32_bf16 v[34:37], v[210:213], v[174:177], v[34:37]
	v_mfma_f32_16x16x32_bf16 v[38:41], v[202:205], v[194:197], v[38:41]
	v_mfma_f32_16x16x32_bf16 v[42:45], v[210:213], v[194:197], v[42:45]
	v_mfma_f32_16x16x32_bf16 v[98:101], v[206:209], v[126:129], v[98:101]
	v_mfma_f32_16x16x32_bf16 v[18:21], v[214:217], v[126:129], v[18:21]
	v_mfma_f32_16x16x32_bf16 v[22:25], v[206:209], v[166:169], v[22:25]
	v_mfma_f32_16x16x32_bf16 v[26:29], v[214:217], v[166:169], v[26:29]
	v_mfma_f32_16x16x32_bf16 v[30:33], v[206:209], v[190:193], v[30:33]
	v_mfma_f32_16x16x32_bf16 v[34:37], v[214:217], v[190:193], v[34:37]
	v_mfma_f32_16x16x32_bf16 v[38:41], v[206:209], v[198:201], v[38:41]
	v_mfma_f32_16x16x32_bf16 v[42:45], v[214:217], v[198:201], v[42:45]
	s_mov_b32 m0, s42
	v_lshl_add_u64 v[170:171], v[188:189], 0, s[52:53]
	s_barrier
	ds_read_b128 v[122:125], v172 offset:49152
	ds_read_b128 v[126:129], v172 offset:50176
	ds_read_b128 v[162:165], v172 offset:51200
	ds_read_b128 v[166:169], v172 offset:52224
	ds_read_b128 v[174:177], v172 offset:53248
	ds_read_b128 v[190:193], v172 offset:54272
	ds_read_b128 v[194:197], v172 offset:55296
	ds_read_b128 v[198:201], v172 offset:56320
	global_load_lds_dwordx4 v[170:171], off
	v_lshl_add_u64 v[170:171], v[218:219], 0, s[52:53]
	s_mov_b32 m0, s43
	s_nop 0
	global_load_lds_dwordx4 v[170:171], off
	s_barrier
	s_waitcnt lgkmcnt(0)
	s_waitcnt lgkmcnt(0)
	v_mfma_f32_16x16x32_bf16 v[130:133], v[90:93], v[122:125], v[130:133]
	v_mfma_f32_16x16x32_bf16 v[134:137], v[114:117], v[122:125], v[134:137]
	v_mfma_f32_16x16x32_bf16 v[146:149], v[90:93], v[162:165], v[146:149]
	v_mfma_f32_16x16x32_bf16 v[150:153], v[114:117], v[162:165], v[150:153]
	v_mfma_f32_16x16x32_bf16 v[154:157], v[90:93], v[174:177], v[154:157]
	v_mfma_f32_16x16x32_bf16 v[158:161], v[114:117], v[174:177], v[158:161]
	v_mfma_f32_16x16x32_bf16 v[2:5], v[90:93], v[194:197], v[2:5]
	v_mfma_f32_16x16x32_bf16 v[6:9], v[114:117], v[194:197], v[6:9]
	v_mfma_f32_16x16x32_bf16 v[130:133], v[94:97], v[126:129], v[130:133]
	v_mfma_f32_16x16x32_bf16 v[134:137], v[118:121], v[126:129], v[134:137]
	v_mfma_f32_16x16x32_bf16 v[146:149], v[94:97], v[166:169], v[146:149]
	v_mfma_f32_16x16x32_bf16 v[150:153], v[118:121], v[166:169], v[150:153]
	v_mfma_f32_16x16x32_bf16 v[154:157], v[94:97], v[190:193], v[154:157]
	v_mfma_f32_16x16x32_bf16 v[158:161], v[118:121], v[190:193], v[158:161]
	v_mfma_f32_16x16x32_bf16 v[2:5], v[94:97], v[198:201], v[2:5]
	v_mfma_f32_16x16x32_bf16 v[6:9], v[118:121], v[198:201], v[6:9]
	s_barrier
	s_add_u32 s52, s30, 0x10180
	s_addc_u32 s53, s31, 0
	s_add_i32 s31, s54, s38
	v_lshl_add_u64 v[90:91], s[52:53], 0, v[140:141]
	s_mov_b32 m0, s31
	s_add_i32 s30, s31, 0x2000
	global_load_lds_dwordx4 v[90:91], off
	v_lshl_add_u64 v[90:91], s[52:53], 0, v[144:145]
	s_mov_b32 m0, s30
	s_nop 0
	global_load_lds_dwordx4 v[90:91], off
	s_waitcnt vmcnt(6)
	s_barrier
	v_mfma_f32_16x16x32_bf16 v[10:13], v[202:205], v[122:125], v[10:13]
	v_mfma_f32_16x16x32_bf16 v[14:17], v[210:213], v[122:125], v[14:17]
	v_mfma_f32_16x16x32_bf16 v[46:49], v[202:205], v[162:165], v[46:49]
	v_mfma_f32_16x16x32_bf16 v[90:93], v[210:213], v[162:165], v[102:105]
	v_mfma_f32_16x16x32_bf16 v[94:97], v[202:205], v[174:177], v[106:109]
	v_mfma_f32_16x16x32_bf16 v[102:105], v[210:213], v[174:177], v[110:113]
	v_mfma_f32_16x16x32_bf16 v[82:85], v[202:205], v[194:197], v[82:85]
	v_mfma_f32_16x16x32_bf16 v[86:89], v[210:213], v[194:197], v[86:89]
	v_mfma_f32_16x16x32_bf16 v[10:13], v[206:209], v[126:129], v[10:13]
	v_mfma_f32_16x16x32_bf16 v[14:17], v[214:217], v[126:129], v[14:17]
	v_mfma_f32_16x16x32_bf16 v[46:49], v[206:209], v[166:169], v[46:49]
	v_mfma_f32_16x16x32_bf16 v[90:93], v[214:217], v[166:169], v[90:93]
	v_mfma_f32_16x16x32_bf16 v[94:97], v[206:209], v[190:193], v[94:97]
	v_mfma_f32_16x16x32_bf16 v[102:105], v[214:217], v[190:193], v[102:105]
	v_mfma_f32_16x16x32_bf16 v[82:85], v[206:209], v[198:201], v[82:85]
	v_mfma_f32_16x16x32_bf16 v[86:89], v[214:217], v[198:201], v[86:89]
	s_barrier
	ds_read_b128 v[106:109], v173
	ds_read_b128 v[110:113], v173 offset:1024
	ds_read_b128 v[114:117], v173 offset:2048
	ds_read_b128 v[118:121], v173 offset:3072
	s_add_u32 s28, s28, 0x40180
	s_addc_u32 s29, s29, 0
	s_mov_b32 m0, s50
	v_lshl_add_u64 v[170:171], s[28:29], 0, v[138:139]
	ds_read_b128 v[122:125], v172
	ds_read_b128 v[126:129], v172 offset:1024
	ds_read_b128 v[162:165], v172 offset:2048
	ds_read_b128 v[166:169], v172 offset:3072
	ds_read_b128 v[174:177], v172 offset:4096
	ds_read_b128 v[190:193], v172 offset:5120
	ds_read_b128 v[194:197], v172 offset:6144
	ds_read_b128 v[198:201], v172 offset:7168
	global_load_lds_dwordx4 v[170:171], off
	v_lshl_add_u64 v[170:171], s[28:29], 0, v[142:143]
	s_mov_b32 m0, s21
	s_nop 0
	global_load_lds_dwordx4 v[170:171], off
	s_waitcnt lgkmcnt(8)
	s_barrier
	s_waitcnt lgkmcnt(0)
	s_waitcnt lgkmcnt(0)
	v_mfma_f32_16x16x32_bf16 v[58:61], v[106:109], v[162:165], v[58:61]
	v_mfma_f32_16x16x32_bf16 v[202:205], v[110:113], v[166:169], v[58:61]
	v_mfma_f32_16x16x32_bf16 v[58:61], v[114:117], v[162:165], v[62:65]
	v_mfma_f32_16x16x32_bf16 v[62:65], v[118:121], v[166:169], v[58:61]
	v_mfma_f32_16x16x32_bf16 v[58:61], v[106:109], v[174:177], v[66:69]
	v_mfma_f32_16x16x32_bf16 v[66:69], v[110:113], v[190:193], v[58:61]
	v_mfma_f32_16x16x32_bf16 v[58:61], v[114:117], v[174:177], v[70:73]
	v_mfma_f32_16x16x32_bf16 v[70:73], v[118:121], v[190:193], v[58:61]
	v_mfma_f32_16x16x32_bf16 v[58:61], v[106:109], v[194:197], v[74:77]
	v_mfma_f32_16x16x32_bf16 v[50:53], v[106:109], v[122:125], v[50:53]
	v_mfma_f32_16x16x32_bf16 v[54:57], v[114:117], v[122:125], v[54:57]
	v_mfma_f32_16x16x32_bf16 v[74:77], v[110:113], v[198:201], v[58:61]
	v_mfma_f32_16x16x32_bf16 v[58:61], v[114:117], v[194:197], v[78:81]
	v_mfma_f32_16x16x32_bf16 v[50:53], v[110:113], v[126:129], v[50:53]
	v_mfma_f32_16x16x32_bf16 v[54:57], v[118:121], v[126:129], v[54:57]
	v_mfma_f32_16x16x32_bf16 v[78:81], v[118:121], v[198:201], v[58:61]
	s_barrier
	s_mov_b32 m0, s47
	v_lshl_add_u64 v[170:171], s[6:7], 0, v[140:141]
	s_nop 0
	ds_read_b128 v[58:61], v220
	ds_read_b128 v[206:209], v220 offset:1024
	ds_read_b128 v[210:213], v220 offset:2048
	ds_read_b128 v[214:217], v220 offset:3072
	global_load_lds_dwordx4 v[170:171], off
	v_lshl_add_u64 v[230:231], s[6:7], 0, v[144:145]
	s_mov_b32 m0, s23
	s_nop 0
	global_load_lds_dwordx4 v[230:231], off
	s_barrier
	s_waitcnt lgkmcnt(0)
	s_waitcnt lgkmcnt(0)
	v_mfma_f32_16x16x32_bf16 v[34:37], v[210:213], v[174:177], v[34:37]
	v_mfma_f32_16x16x32_bf16 v[22:25], v[58:61], v[162:165], v[22:25]
	v_mfma_f32_16x16x32_bf16 v[26:29], v[210:213], v[162:165], v[26:29]
	v_mfma_f32_16x16x32_bf16 v[162:165], v[214:217], v[190:193], v[34:37]
	v_mfma_f32_16x16x32_bf16 v[34:37], v[58:61], v[194:197], v[38:41]
	v_mfma_f32_16x16x32_bf16 v[98:101], v[58:61], v[122:125], v[98:101]
	v_mfma_f32_16x16x32_bf16 v[18:21], v[210:213], v[122:125], v[18:21]
	v_mfma_f32_16x16x32_bf16 v[30:33], v[58:61], v[174:177], v[30:33]
	v_mfma_f32_16x16x32_bf16 v[38:41], v[206:209], v[198:201], v[34:37]
	v_mfma_f32_16x16x32_bf16 v[34:37], v[210:213], v[194:197], v[42:45]
	v_mfma_f32_16x16x32_bf16 v[98:101], v[206:209], v[126:129], v[98:101]
	v_mfma_f32_16x16x32_bf16 v[18:21], v[214:217], v[126:129], v[18:21]
	v_mfma_f32_16x16x32_bf16 v[22:25], v[206:209], v[166:169], v[22:25]
	v_mfma_f32_16x16x32_bf16 v[26:29], v[214:217], v[166:169], v[26:29]
	v_mfma_f32_16x16x32_bf16 v[30:33], v[206:209], v[190:193], v[30:33]
	v_mfma_f32_16x16x32_bf16 v[166:169], v[214:217], v[198:201], v[34:37]
	s_mov_b32 m0, s3
	v_lshl_add_u64 v[252:253], s[24:25], 0, v[138:139]
	s_barrier
	ds_read_b128 v[34:37], v172 offset:16384
	ds_read_b128 v[42:45], v172 offset:17408
	ds_read_b128 v[122:125], v172 offset:18432
	ds_read_b128 v[126:129], v172 offset:19456
	ds_read_b128 v[174:177], v172 offset:20480
	ds_read_b128 v[190:193], v172 offset:21504
	ds_read_b128 v[194:197], v172 offset:22528
	ds_read_b128 v[198:201], v172 offset:23552
	global_load_lds_dwordx4 v[252:253], off
	v_lshl_add_u64 v[246:247], s[24:25], 0, v[142:143]
	s_mov_b32 m0, s39
	s_nop 0
	global_load_lds_dwordx4 v[246:247], off
	s_barrier
	s_waitcnt lgkmcnt(0)
	s_waitcnt lgkmcnt(0)
	v_mfma_f32_16x16x32_bf16 v[130:133], v[106:109], v[34:37], v[130:133]
	v_mfma_f32_16x16x32_bf16 v[218:221], v[110:113], v[42:45], v[130:133]
	v_mfma_f32_16x16x32_bf16 v[130:133], v[114:117], v[34:37], v[134:137]
	v_mfma_f32_16x16x32_bf16 v[222:225], v[118:121], v[42:45], v[130:133]
	v_mfma_f32_16x16x32_bf16 v[130:133], v[106:109], v[122:125], v[146:149]
	v_mfma_f32_16x16x32_bf16 v[146:149], v[110:113], v[126:129], v[130:133]
	v_mfma_f32_16x16x32_bf16 v[130:133], v[114:117], v[122:125], v[150:153]
	v_mfma_f32_16x16x32_bf16 v[150:153], v[118:121], v[126:129], v[130:133]
	v_mfma_f32_16x16x32_bf16 v[130:133], v[106:109], v[174:177], v[154:157]
	v_mfma_f32_16x16x32_bf16 v[154:157], v[110:113], v[190:193], v[130:133]
	v_mfma_f32_16x16x32_bf16 v[130:133], v[114:117], v[174:177], v[158:161]
	v_mfma_f32_16x16x32_bf16 v[2:5], v[106:109], v[194:197], v[2:5]
	v_mfma_f32_16x16x32_bf16 v[6:9], v[114:117], v[194:197], v[6:9]
	v_mfma_f32_16x16x32_bf16 v[158:161], v[118:121], v[190:193], v[130:133]
	v_mfma_f32_16x16x32_bf16 v[2:5], v[110:113], v[198:201], v[2:5]
	v_mfma_f32_16x16x32_bf16 v[6:9], v[118:121], v[198:201], v[6:9]
	s_barrier
	s_add_u32 s28, s6, 0x10000
	s_addc_u32 s29, s7, 0
	s_mov_b32 m0, s48
	v_lshl_add_u64 v[106:107], s[28:29], 0, v[140:141]
	global_load_lds_dwordx4 v[106:107], off
	v_lshl_add_u64 v[106:107], s[28:29], 0, v[144:145]
	s_mov_b32 m0, s46
	s_nop 0
	global_load_lds_dwordx4 v[106:107], off
	s_waitcnt vmcnt(6)
	s_barrier
	v_mfma_f32_16x16x32_bf16 v[10:13], v[58:61], v[34:37], v[10:13]
	v_mfma_f32_16x16x32_bf16 v[226:229], v[206:209], v[42:45], v[10:13]
	v_mfma_f32_16x16x32_bf16 v[10:13], v[210:213], v[34:37], v[14:17]
	v_mfma_f32_16x16x32_bf16 v[14:17], v[214:217], v[42:45], v[10:13]
	v_mfma_f32_16x16x32_bf16 v[10:13], v[58:61], v[122:125], v[46:49]
	v_mfma_f32_16x16x32_bf16 v[248:251], v[206:209], v[126:129], v[10:13]
	v_mfma_f32_16x16x32_bf16 v[10:13], v[210:213], v[122:125], v[90:93]
	v_mfma_f32_16x16x32_bf16 v[236:239], v[214:217], v[126:129], v[10:13]
	v_mfma_f32_16x16x32_bf16 v[10:13], v[58:61], v[174:177], v[94:97]
	v_mfma_f32_16x16x32_bf16 v[186:189], v[206:209], v[190:193], v[10:13]
	v_mfma_f32_16x16x32_bf16 v[10:13], v[210:213], v[174:177], v[102:105]
	v_mfma_f32_16x16x32_bf16 v[174:177], v[214:217], v[190:193], v[10:13]
	v_mfma_f32_16x16x32_bf16 v[10:13], v[58:61], v[194:197], v[82:85]
	v_mfma_f32_16x16x32_bf16 v[190:193], v[206:209], v[198:201], v[10:13]
	v_mfma_f32_16x16x32_bf16 v[10:13], v[210:213], v[194:197], v[86:89]
	v_mfma_f32_16x16x32_bf16 v[194:197], v[214:217], v[198:201], v[10:13]
	s_barrier
	ds_read_b128 v[86:89], v232
	ds_read_b128 v[94:97], v232 offset:1024
	ds_read_b128 v[102:105], v232 offset:2048
	ds_read_b128 v[198:201], v232 offset:3072
	s_add_u32 s28, s24, 0x40000
	s_addc_u32 s29, s25, 0
	s_mov_b32 m0, s40
	v_lshl_add_u64 v[34:35], s[28:29], 0, v[138:139]
	ds_read_b128 v[10:13], v172 offset:32768
	ds_read_b128 v[46:49], v172 offset:33792
	ds_read_b128 v[82:85], v172 offset:34816
	ds_read_b128 v[90:93], v172 offset:35840
	ds_read_b128 v[110:113], v172 offset:36864
	ds_read_b128 v[206:209], v172 offset:37888
	ds_read_b128 v[210:213], v172 offset:38912
	ds_read_b128 v[214:217], v172 offset:39936
	global_load_lds_dwordx4 v[34:35], off
	v_lshl_add_u64 v[34:35], s[28:29], 0, v[142:143]
	s_mov_b32 m0, s41
	s_nop 0
	global_load_lds_dwordx4 v[34:35], off
	s_waitcnt lgkmcnt(8)
	s_barrier
	s_waitcnt lgkmcnt(0)
	s_waitcnt lgkmcnt(0)
	v_mfma_f32_16x16x32_bf16 v[34:37], v[86:89], v[10:13], v[50:53]
	v_mfma_f32_16x16x32_bf16 v[130:133], v[94:97], v[46:49], v[34:37]
	v_mfma_f32_16x16x32_bf16 v[34:37], v[102:105], v[10:13], v[54:57]
	v_mfma_f32_16x16x32_bf16 v[58:61], v[198:201], v[46:49], v[34:37]
	v_mfma_f32_16x16x32_bf16 v[34:37], v[86:89], v[82:85], v[202:205]
	v_mfma_f32_16x16x32_bf16 v[122:125], v[94:97], v[90:93], v[34:37]
	v_mfma_f32_16x16x32_bf16 v[34:37], v[102:105], v[82:85], v[62:65]
	v_mfma_f32_16x16x32_bf16 v[50:53], v[198:201], v[90:93], v[34:37]
	v_mfma_f32_16x16x32_bf16 v[34:37], v[86:89], v[110:113], v[66:69]
	v_mfma_f32_16x16x32_bf16 v[114:117], v[94:97], v[206:209], v[34:37]
	v_mfma_f32_16x16x32_bf16 v[34:37], v[102:105], v[110:113], v[70:73]
	v_mfma_f32_16x16x32_bf16 v[42:45], v[198:201], v[206:209], v[34:37]
	v_mfma_f32_16x16x32_bf16 v[34:37], v[86:89], v[210:213], v[74:77]
	v_mfma_f32_16x16x32_bf16 v[106:109], v[94:97], v[214:217], v[34:37]
	v_mfma_f32_16x16x32_bf16 v[34:37], v[102:105], v[210:213], v[78:81]
	v_mfma_f32_16x16x32_bf16 v[34:37], v[198:201], v[214:217], v[34:37]
	s_barrier
	s_mov_b32 m0, s51
	v_lshl_add_u64 v[54:55], v[170:171], 0, s[0:1]
	ds_read_b128 v[70:73], v233
	ds_read_b128 v[74:77], v233 offset:1024
	ds_read_b128 v[78:81], v233 offset:2048
	ds_read_b128 v[202:205], v233 offset:3072
	global_load_lds_dwordx4 v[54:55], off
	v_lshl_add_u64 v[54:55], v[230:231], 0, s[0:1]
	s_mov_b32 m0, s49
	s_nop 0
	global_load_lds_dwordx4 v[54:55], off
	s_barrier
	s_waitcnt lgkmcnt(0)
	s_waitcnt lgkmcnt(0)
	v_mfma_f32_16x16x32_bf16 v[54:57], v[70:73], v[10:13], v[98:101]
	v_mfma_f32_16x16x32_bf16 v[10:13], v[78:81], v[10:13], v[18:21]
	v_mfma_f32_16x16x32_bf16 v[62:65], v[202:205], v[46:49], v[10:13]
	v_mfma_f32_16x16x32_bf16 v[10:13], v[70:73], v[82:85], v[22:25]
	v_mfma_f32_16x16x32_bf16 v[126:129], v[74:77], v[90:93], v[10:13]
	v_mfma_f32_16x16x32_bf16 v[10:13], v[78:81], v[82:85], v[26:29]
	v_mfma_f32_16x16x32_bf16 v[134:137], v[74:77], v[46:49], v[54:57]
	v_mfma_f32_16x16x32_bf16 v[54:57], v[202:205], v[90:93], v[10:13]
	v_mfma_f32_16x16x32_bf16 v[10:13], v[70:73], v[110:113], v[30:33]
	v_mfma_f32_16x16x32_bf16 v[118:121], v[74:77], v[206:209], v[10:13]
	v_mfma_f32_16x16x32_bf16 v[10:13], v[78:81], v[110:113], v[162:165]
	v_mfma_f32_16x16x32_bf16 v[46:49], v[202:205], v[206:209], v[10:13]
	v_mfma_f32_16x16x32_bf16 v[10:13], v[70:73], v[210:213], v[38:41]
	v_mfma_f32_16x16x32_bf16 v[110:113], v[74:77], v[214:217], v[10:13]
	v_mfma_f32_16x16x32_bf16 v[10:13], v[78:81], v[210:213], v[166:169]
	v_mfma_f32_16x16x32_bf16 v[38:41], v[202:205], v[214:217], v[10:13]
	s_mov_b32 m0, s42
	s_nop 4
	v_lshl_add_u64 v[10:11], v[252:253], 0, s[0:1]
	s_barrier
	ds_read_b128 v[22:25], v172 offset:49152
	ds_read_b128 v[30:33], v172 offset:50176
	ds_read_b128 v[162:165], v172 offset:51200
	ds_read_b128 v[166:169], v172 offset:52224
	ds_read_b128 v[206:209], v172 offset:53248
	ds_read_b128 v[210:213], v172 offset:54272
	ds_read_b128 v[214:217], v172 offset:55296
	ds_read_b128 v[230:233], v172 offset:56320
	global_load_lds_dwordx4 v[10:11], off
	v_lshl_add_u64 v[10:11], v[246:247], 0, s[0:1]
	s_mov_b32 m0, s43
	s_nop 0
	global_load_lds_dwordx4 v[10:11], off
	s_barrier
	s_waitcnt lgkmcnt(0)
	s_waitcnt lgkmcnt(0)
	v_mfma_f32_16x16x32_bf16 v[10:13], v[86:89], v[22:25], v[218:221]
	v_mfma_f32_16x16x32_bf16 v[98:101], v[94:97], v[30:33], v[10:13]
	v_mfma_f32_16x16x32_bf16 v[10:13], v[102:105], v[22:25], v[222:225]
	v_mfma_f32_16x16x32_bf16 v[26:29], v[198:201], v[30:33], v[10:13]
	v_mfma_f32_16x16x32_bf16 v[10:13], v[86:89], v[162:165], v[146:149]
	v_mfma_f32_16x16x32_bf16 v[90:93], v[94:97], v[166:169], v[10:13]
	v_mfma_f32_16x16x32_bf16 v[10:13], v[102:105], v[162:165], v[150:153]
	v_mfma_f32_16x16x32_bf16 v[18:21], v[198:201], v[166:169], v[10:13]
	v_mfma_f32_16x16x32_bf16 v[10:13], v[86:89], v[206:209], v[154:157]
	v_mfma_f32_16x16x32_bf16 v[2:5], v[86:89], v[214:217], v[2:5]
	v_mfma_f32_16x16x32_bf16 v[82:85], v[94:97], v[210:213], v[10:13]
	v_mfma_f32_16x16x32_bf16 v[10:13], v[102:105], v[206:209], v[158:161]
	v_mfma_f32_16x16x32_bf16 v[66:69], v[94:97], v[230:233], v[2:5]
	v_mfma_f32_16x16x32_bf16 v[2:5], v[102:105], v[214:217], v[6:9]
	v_mfma_f32_16x16x32_bf16 v[10:13], v[198:201], v[210:213], v[10:13]
	v_mfma_f32_16x16x32_bf16 v[2:5], v[198:201], v[230:233], v[2:5]
	s_barrier
	s_add_u32 s6, s6, 0x10080
	s_addc_u32 s7, s7, 0
	s_mov_b32 m0, s31
	v_lshl_add_u64 v[6:7], s[6:7], 0, v[140:141]
	global_load_lds_dwordx4 v[6:7], off
	v_lshl_add_u64 v[6:7], s[6:7], 0, v[144:145]
	s_mov_b32 m0, s30
	s_nop 0
	global_load_lds_dwordx4 v[6:7], off
	s_waitcnt vmcnt(6)
	s_barrier
	v_mfma_f32_16x16x32_bf16 v[6:9], v[70:73], v[22:25], v[226:229]
	v_mfma_f32_16x16x32_bf16 v[102:105], v[74:77], v[30:33], v[6:9]
	v_mfma_f32_16x16x32_bf16 v[6:9], v[78:81], v[22:25], v[14:17]
	v_mfma_f32_16x16x32_bf16 v[30:33], v[202:205], v[30:33], v[6:9]
	v_mfma_f32_16x16x32_bf16 v[6:9], v[70:73], v[162:165], v[248:251]
	v_mfma_f32_16x16x32_bf16 v[94:97], v[74:77], v[166:169], v[6:9]
	v_mfma_f32_16x16x32_bf16 v[6:9], v[78:81], v[162:165], v[236:239]
	v_mfma_f32_16x16x32_bf16 v[22:25], v[202:205], v[166:169], v[6:9]
	v_mfma_f32_16x16x32_bf16 v[6:9], v[70:73], v[206:209], v[186:189]
	v_mfma_f32_16x16x32_bf16 v[86:89], v[74:77], v[210:213], v[6:9]
	v_mfma_f32_16x16x32_bf16 v[6:9], v[78:81], v[206:209], v[174:177]
	v_mfma_f32_16x16x32_bf16 v[14:17], v[202:205], v[210:213], v[6:9]
	v_mfma_f32_16x16x32_bf16 v[6:9], v[70:73], v[214:217], v[190:193]
	v_mfma_f32_16x16x32_bf16 v[70:73], v[74:77], v[230:233], v[6:9]
	v_mfma_f32_16x16x32_bf16 v[6:9], v[78:81], v[214:217], v[194:197]
	v_mfma_f32_16x16x32_bf16 v[6:9], v[202:205], v[230:233], v[6:9]
	v_mov_b32_e32 v74, v178
	s_barrier
	s_add_i32 s45, s45, s34
	v_ashrrev_i32_e32 v75, 2, v74
	v_and_b32_e32 v75, 0xffffffc0, v75
	v_lshl_add_u32 v75, s2, 8, v75
	v_and_or_b32 v148, v74, 15, v75
	v_lshrrev_b32_e32 v74, 1, v74
	v_and_b32_e32 v74, 0x78, v74
	v_lshl_or_b32 v150, s33, 7, v74
	v_ashrrev_i32_e32 v151, 31, v150
	v_lshlrev_b64 v[146:147], 2, v[150:151]
	v_lshl_add_u64 v[154:155], s[10:11], 0, v[146:147]
	global_load_dwordx4 v[158:161], v[154:155], off
	v_lshl_add_u64 v[152:153], s[16:17], 0, v[146:147]
	v_lshl_add_u64 v[156:157], s[8:9], 0, v[146:147]
	global_load_dwordx4 v[78:81], v[152:153], off
	global_load_dwordx4 v[74:77], v[156:157], off
	v_mov_b32_e32 v166, v148
	s_mov_b32 s2, 0xc1000000
	v_ashrrev_i32_e32 v167, 31, v166
	global_load_dwordx4 v[236:239], v[152:153], off offset:16
	global_load_dwordx4 v[246:249], v[156:157], off offset:16
	global_load_dwordx4 v[250:253], v[154:155], off offset:16
	v_lshlrev_b64 v[146:147], 11, v[166:167]
	v_lshl_add_u64 v[168:169], s[14:15], 0, v[146:147]
	v_lshlrev_b64 v[146:147], 1, v[150:151]
	v_lshl_add_u64 v[168:169], v[168:169], 0, v[146:147]
	v_mov_b32_e32 v230, v168
	v_mov_b32_e32 v231, v169
	v_mov_b32_e32 v232, 0x8000
	v_mov_b32_e32 v233, 0
	global_load_dwordx2 v[174:175], v[230:231], off
	global_load_dwordx2 v[202:203], v[230:231], off offset:8
	v_lshl_add_u64 v[230:231], v[230:231], 0, v[232:233]
	global_load_dwordx2 v[176:177], v[230:231], off
	global_load_dwordx2 v[204:205], v[230:231], off offset:8
	v_lshl_add_u64 v[230:231], v[230:231], 0, v[232:233]
	global_load_dwordx2 v[190:191], v[230:231], off
	global_load_dwordx2 v[206:207], v[230:231], off offset:8
	v_lshl_add_u64 v[230:231], v[230:231], 0, v[232:233]
	global_load_dwordx2 v[192:193], v[230:231], off
	global_load_dwordx2 v[208:209], v[230:231], off offset:8
	v_mov_b32_e32 v232, 0x28000
	v_lshl_add_u64 v[230:231], v[230:231], 0, v[232:233]
	v_mov_b32_e32 v232, 0x8000
	global_load_dwordx2 v[194:195], v[230:231], off
	global_load_dwordx2 v[210:211], v[230:231], off offset:8
	v_lshl_add_u64 v[230:231], v[230:231], 0, v[232:233]
	global_load_dwordx2 v[196:197], v[230:231], off
	global_load_dwordx2 v[212:213], v[230:231], off offset:8
	v_lshl_add_u64 v[230:231], v[230:231], 0, v[232:233]
	global_load_dwordx2 v[198:199], v[230:231], off
	global_load_dwordx2 v[214:215], v[230:231], off offset:8
	v_lshl_add_u64 v[230:231], v[230:231], 0, v[232:233]
	global_load_dwordx2 v[200:201], v[230:231], off
	global_load_dwordx2 v[216:217], v[230:231], off offset:8
	s_mov_b32 s33, s20
	s_mov_b64 s[30:31], s[26:27]
	s_mov_b64 s[28:29], s[24:25]
	s_waitcnt vmcnt(0)
	v_max_f32_e64 v146, -v158, -v158
	v_max_f32_e32 v162, 0, v146
	v_mul_f32_e64 v146, |v158|, s72
	v_exp_f32_e32 v146, v146
	v_add_f32_e32 v130, v130, v78
	v_add_f32_e32 v131, v131, v79
	v_mul_f32_e32 v130, 0xbfb8aa3b, v130
	v_add_f32_e32 v146, 1.0, v146
	v_cmp_gt_f32_e32 vcc, s71, v146
	v_mul_f32_e32 v131, 0xbfb8aa3b, v131
	v_exp_f32_e32 v130, v130
	v_cndmask_b32_e64 v147, 0, 32, vcc
	v_ldexp_f32 v146, v146, v147
	v_log_f32_e32 v146, v146
	v_exp_f32_e32 v131, v131
	v_add_f32_e32 v130, 1.0, v130
	v_rcp_f32_e32 v170, v130
	v_mul_f32_e32 v147, 0x3f317217, v146
	v_fma_f32 v147, v146, s73, -v147
	v_fmac_f32_e32 v147, 0x3377d1cf, v146
	v_fmac_f32_e32 v147, 0x3f317217, v146
	v_cmp_lt_f32_e64 s[6:7], |v146|, s74
	v_add_f32_e32 v131, 1.0, v131
	v_rcp_f32_e32 v171, v131
	v_cndmask_b32_e64 v146, v146, v147, s[6:7]
	v_cndmask_b32_e32 v147, 0, v243, vcc
	v_sub_f32_e32 v164, v146, v147
	v_max_f32_e64 v146, -v159, -v159
	v_max_f32_e32 v163, 0, v146
	v_mul_f32_e64 v146, |v159|, s72
	v_exp_f32_e32 v146, v146
	v_add_f32_e32 v130, v134, v74
	v_add_f32_e32 v131, v135, v75
	v_mul_f32_e32 v130, 0xbfb8aa3b, v130
	v_add_f32_e32 v146, 1.0, v146
	v_cmp_gt_f32_e32 vcc, s71, v146
	v_mul_f32_e32 v131, 0xbfb8aa3b, v131
	v_exp_f32_e32 v130, v130
	v_cndmask_b32_e64 v147, 0, 32, vcc
	v_ldexp_f32 v146, v146, v147
	v_log_f32_e32 v146, v146
	v_exp_f32_e32 v131, v131
	v_add_f32_e32 v130, 1.0, v130
	v_rcp_f32_e32 v130, v130
	v_mul_f32_e32 v147, 0x3f317217, v146
	v_fma_f32 v147, v146, s73, -v147
	v_fmac_f32_e32 v147, 0x3377d1cf, v146
	v_fmac_f32_e32 v147, 0x3f317217, v146
	v_cmp_lt_f32_e64 s[6:7], |v146|, s74
	v_add_f32_e32 v131, 1.0, v131
	v_rcp_f32_e32 v131, v131
	v_cndmask_b32_e64 v146, v146, v147, s[6:7]
	v_cndmask_b32_e32 v147, 0, v243, vcc
	v_sub_f32_e32 v165, v146, v147
	v_max_f32_e64 v146, -v160, -v160
	v_max_f32_e32 v158, 0, v146
	v_mul_f32_e64 v146, |v160|, s72
	v_exp_f32_e32 v146, v146
	v_pk_add_f32 v[134:135], v[162:163], v[164:165]
	v_add_f32_e32 v122, v122, v78
	v_pk_mul_f32 v[134:135], v[134:135], s[2:3] op_sel_hi:[1,0]
	v_add_f32_e32 v146, 1.0, v146
	v_cmp_gt_f32_e32 vcc, s71, v146
	v_pk_mul_f32 v[162:163], v[170:171], v[134:135]
	v_add_f32_e32 v123, v123, v79
	v_cndmask_b32_e64 v147, 0, 32, vcc
	v_ldexp_f32 v146, v146, v147
	v_log_f32_e32 v146, v146
	v_add_f32_e32 v149, v162, v162
	v_mul_f32_e32 v149, 0x3fb8aa3b, v149
	v_exp_f32_e32 v149, v149
	v_mul_f32_e32 v147, 0x3f317217, v146
	v_fma_f32 v147, v146, s73, -v147
	v_fmac_f32_e32 v147, 0x3377d1cf, v146
	v_fmac_f32_e32 v147, 0x3f317217, v146
	v_cmp_lt_f32_e64 s[6:7], |v146|, s74
	v_sub_f32_e32 v149, 1.0, v149
	v_max_f32_e32 v149, 0, v149
	v_cndmask_b32_e64 v146, v146, v147, s[6:7]
	v_cndmask_b32_e32 v147, 0, v243, vcc
	v_sub_f32_e32 v160, v146, v147
	v_max_f32_e64 v146, -v161, -v161
	v_max_f32_e32 v159, 0, v146
	v_mul_f32_e64 v146, |v161|, s72
	v_exp_f32_e32 v146, v146
	v_sqrt_f32_e32 v164, v149
	v_add_f32_e32 v149, v163, v163
	v_mul_f32_e32 v149, 0x3fb8aa3b, v149
	v_add_f32_e32 v146, 1.0, v146
	v_cmp_gt_f32_e32 vcc, s71, v146
	v_exp_f32_e32 v149, v149
	v_mul_f32_e32 v122, 0xbfb8aa3b, v122
	v_cndmask_b32_e64 v147, 0, 32, vcc
	v_ldexp_f32 v146, v146, v147
	v_log_f32_e32 v146, v146
	v_sub_f32_e32 v149, 1.0, v149
	v_max_f32_e32 v149, 0, v149
	v_sqrt_f32_e32 v165, v149
	v_mul_f32_e32 v147, 0x3f317217, v146
	v_fma_f32 v147, v146, s73, -v147
	v_fmac_f32_e32 v147, 0x3377d1cf, v146
	v_fmac_f32_e32 v147, 0x3f317217, v146
	v_cmp_lt_f32_e64 s[6:7], |v146|, s74
	v_pk_mul_f32 v[130:131], v[130:131], v[164:165]
	v_mul_f32_e32 v123, 0xbfb8aa3b, v123
	v_cndmask_b32_e64 v146, v146, v147, s[6:7]
	v_cndmask_b32_e32 v147, 0, v243, vcc
	v_sub_f32_e32 v161, v146, v147
	v_exp_f32_e32 v122, v122
	v_exp_f32_e32 v123, v123
	v_add_f32_e32 v126, v126, v74
	v_add_f32_e32 v127, v127, v75
	v_add_f32_e32 v122, 1.0, v122
	v_add_f32_e32 v123, 1.0, v123
	v_rcp_f32_e32 v122, v122
	v_rcp_f32_e32 v123, v123
	v_mul_f32_e32 v126, 0xbfb8aa3b, v126
	v_mul_f32_e32 v127, 0xbfb8aa3b, v127
	v_exp_f32_e32 v126, v126
	v_exp_f32_e32 v127, v127
	v_add_f32_e32 v114, v114, v78
	v_add_f32_e32 v115, v115, v79
	v_add_f32_e32 v126, 1.0, v126
	v_add_f32_e32 v127, 1.0, v127
	v_rcp_f32_e32 v126, v126
	v_rcp_f32_e32 v127, v127
	v_mul_f32_e32 v114, 0xbfb8aa3b, v114
	v_mul_f32_e32 v115, 0xbfb8aa3b, v115
	v_exp_f32_e32 v114, v114
	v_exp_f32_e32 v115, v115
	v_add_f32_e32 v118, v118, v74
	v_add_f32_e32 v119, v119, v75
	v_add_f32_e32 v114, 1.0, v114
	v_add_f32_e32 v115, 1.0, v115
	v_rcp_f32_e32 v114, v114
	v_rcp_f32_e32 v115, v115
	v_mul_f32_e32 v118, 0xbfb8aa3b, v118
	v_mul_f32_e32 v119, 0xbfb8aa3b, v119
	v_exp_f32_e32 v118, v118
	v_exp_f32_e32 v119, v119
	v_add_f32_e32 v106, v106, v78
	v_add_f32_e32 v107, v107, v79
	v_add_f32_e32 v118, 1.0, v118
	v_add_f32_e32 v119, 1.0, v119
	v_rcp_f32_e32 v118, v118
	v_rcp_f32_e32 v119, v119
	v_mul_f32_e32 v106, 0xbfb8aa3b, v106
	v_mul_f32_e32 v107, 0xbfb8aa3b, v107
	v_exp_f32_e32 v106, v106
	v_exp_f32_e32 v107, v107
	v_add_f32_e32 v110, v110, v74
	v_add_f32_e32 v111, v111, v75
	v_add_f32_e32 v106, 1.0, v106
	v_add_f32_e32 v107, 1.0, v107
	v_rcp_f32_e32 v106, v106
	v_rcp_f32_e32 v107, v107
	v_mul_f32_e32 v110, 0xbfb8aa3b, v110
	v_mul_f32_e32 v111, 0xbfb8aa3b, v111
	v_exp_f32_e32 v110, v110
	v_exp_f32_e32 v111, v111
	v_add_f32_e32 v98, v98, v78
	v_add_f32_e32 v99, v99, v79
	v_add_f32_e32 v110, 1.0, v110
	v_add_f32_e32 v111, 1.0, v111
	v_rcp_f32_e32 v110, v110
	v_rcp_f32_e32 v111, v111
	v_mul_f32_e32 v98, 0xbfb8aa3b, v98
	v_mul_f32_e32 v99, 0xbfb8aa3b, v99
	v_exp_f32_e32 v98, v98
	v_exp_f32_e32 v99, v99
	v_add_f32_e32 v102, v102, v74
	v_add_f32_e32 v103, v103, v75
	v_add_f32_e32 v98, 1.0, v98
	v_add_f32_e32 v99, 1.0, v99
	v_rcp_f32_e32 v98, v98
	v_rcp_f32_e32 v99, v99
	v_mul_f32_e32 v102, 0xbfb8aa3b, v102
	v_mul_f32_e32 v103, 0xbfb8aa3b, v103
	v_exp_f32_e32 v102, v102
	v_exp_f32_e32 v103, v103
	v_add_f32_e32 v90, v90, v78
	v_add_f32_e32 v91, v91, v79
	v_add_f32_e32 v102, 1.0, v102
	v_add_f32_e32 v103, 1.0, v103
	v_rcp_f32_e32 v102, v102
	v_rcp_f32_e32 v103, v103
	v_mul_f32_e32 v90, 0xbfb8aa3b, v90
	s_waitcnt vmcnt(0)
	v_mov_b32_e32 v168, v174
	v_mov_b32_e32 v169, v175
	v_lshlrev_b32_e32 v170, 16, v168
	v_and_b32_e32 v171, 0xffff0000, v168
	v_pk_mul_f32 v[164:165], v[130:131], v[170:171]
	v_add_f32_e32 v131, v136, v76
	v_mul_f32_e32 v131, 0xbfb8aa3b, v131
	v_exp_f32_e32 v131, v131
	v_add_f32_e32 v130, v132, v80
	v_mul_f32_e32 v130, 0xbfb8aa3b, v130
	v_exp_f32_e32 v130, v130
	v_add_f32_e32 v131, 1.0, v131
	v_rcp_f32_e32 v136, v131
	v_add_f32_e32 v131, v133, v81
	v_mul_f32_e32 v131, 0xbfb8aa3b, v131
	v_exp_f32_e32 v131, v131
	v_add_f32_e32 v132, v137, v77
	v_mul_f32_e32 v132, 0xbfb8aa3b, v132
	v_exp_f32_e32 v132, v132
	v_add_f32_e32 v130, 1.0, v130
	v_add_f32_e32 v131, 1.0, v131
	v_rcp_f32_e32 v130, v130
	v_rcp_f32_e32 v131, v131
	v_add_f32_e32 v132, 1.0, v132
	v_rcp_f32_e32 v137, v132
	v_pk_add_f32 v[132:133], v[158:159], v[160:161]
	v_lshlrev_b32_e32 v160, 16, v169
	v_pk_mul_f32 v[132:133], v[132:133], s[2:3] op_sel_hi:[1,0]
	v_and_b32_e32 v161, 0xffff0000, v169
	v_pk_mul_f32 v[130:131], v[130:131], v[132:133]
	v_mul_f32_e32 v91, 0xbfb8aa3b, v91
	v_add_f32_e32 v149, v130, v130
	v_mul_f32_e32 v149, 0x3fb8aa3b, v149
	v_exp_f32_e32 v149, v149
	v_exp_f32_e32 v90, v90
	v_exp_f32_e32 v91, v91
	v_add_f32_e32 v94, v94, v74
	v_sub_f32_e32 v149, 1.0, v149
	v_max_f32_e32 v149, 0, v149
	v_sqrt_f32_e32 v158, v149
	v_add_f32_e32 v149, v131, v131
	v_mul_f32_e32 v149, 0x3fb8aa3b, v149
	v_exp_f32_e32 v149, v149
	v_add_f32_e32 v90, 1.0, v90
	v_add_f32_e32 v91, 1.0, v91
	v_rcp_f32_e32 v90, v90
	v_sub_f32_e32 v149, 1.0, v149
	v_max_f32_e32 v149, 0, v149
	v_sqrt_f32_e32 v159, v149
	v_rcp_f32_e32 v91, v91
	v_add_f32_e32 v95, v95, v75
	v_mul_f32_e32 v94, 0xbfb8aa3b, v94
	v_pk_mul_f32 v[136:137], v[136:137], v[158:159]
	v_mul_f32_e32 v95, 0xbfb8aa3b, v95
	v_pk_mul_f32 v[158:159], v[136:137], v[160:161]
	v_cvt_pk_bf16_f32 v161, v130, v131
	v_mov_b64_e32 v[130:131], s[18:19]
	v_cvt_pk_bf16_f32 v160, v162, v163
	v_mad_i64_i32 v[162:163], s[6:7], v166, s84, v[130:131]
	v_lshl_add_u64 v[162:163], v[162:163], 0, v[146:147]
	v_add_co_u32_e32 v162, vcc, s69, v162
	v_add_u32_e32 v136, 16, v166
	s_nop 0
	v_addc_co_u32_e32 v163, vcc, 0, v163, vcc
	v_mov_b32_e32 v220, v160
	v_mov_b32_e32 v221, v161
	v_cvt_pk_bf16_f32 v160, v164, v165
	v_cvt_pk_bf16_f32 v161, v158, v159
	v_mov_b32_e32 v224, v160
	v_mov_b32_e32 v225, v161
	v_pk_mul_f32 v[160:161], v[122:123], v[134:135]
	v_ashrrev_i32_e32 v137, 31, v136
	v_lshlrev_b64 v[158:159], 11, v[136:137]
	v_lshl_add_u64 v[158:159], s[14:15], 0, v[158:159]
	v_lshl_add_u64 v[158:159], v[158:159], 0, v[146:147]
	s_nop 0
	v_add_f32_e32 v122, v160, v160
	v_add_f32_e32 v123, v161, v161
	v_mul_f32_e32 v122, 0x3fb8aa3b, v122
	v_mul_f32_e32 v123, 0x3fb8aa3b, v123
	v_exp_f32_e32 v122, v122
	v_exp_f32_e32 v123, v123
	v_exp_f32_e32 v94, v94
	v_exp_f32_e32 v95, v95
	v_sub_f32_e32 v122, 1.0, v122
	v_sub_f32_e32 v123, 1.0, v123
	v_max_f32_e32 v122, 0, v122
	v_max_f32_e32 v123, 0, v123
	v_sqrt_f32_e32 v122, v122
	v_sqrt_f32_e32 v123, v123
	v_add_f32_e32 v94, 1.0, v94
	v_add_f32_e32 v95, 1.0, v95
	v_rcp_f32_e32 v94, v94
	v_pk_mul_f32 v[122:123], v[126:127], v[122:123]
	v_rcp_f32_e32 v95, v95
	v_add_f32_e32 v82, v82, v78
	v_add_f32_e32 v83, v83, v79
	v_mul_f32_e32 v82, 0xbfb8aa3b, v82
	v_mul_f32_e32 v83, 0xbfb8aa3b, v83
	v_exp_f32_e32 v82, v82
	v_exp_f32_e32 v83, v83
	v_add_f32_e32 v86, v86, v74
	v_add_f32_e32 v87, v87, v75
	v_add_f32_e32 v82, 1.0, v82
	v_add_f32_e32 v83, 1.0, v83
	v_rcp_f32_e32 v82, v82
	v_rcp_f32_e32 v83, v83
	v_mul_f32_e32 v86, 0xbfb8aa3b, v86
	v_mul_f32_e32 v87, 0xbfb8aa3b, v87
	v_exp_f32_e32 v86, v86
	v_exp_f32_e32 v87, v87
	v_add_f32_e32 v66, v66, v78
	v_add_f32_e32 v67, v67, v79
	v_add_f32_e32 v86, 1.0, v86
	v_add_f32_e32 v87, 1.0, v87
	v_rcp_f32_e32 v86, v86
	v_rcp_f32_e32 v87, v87
	v_mul_f32_e32 v66, 0xbfb8aa3b, v66
	v_mul_f32_e32 v67, 0xbfb8aa3b, v67
	v_exp_f32_e32 v66, v66
	v_exp_f32_e32 v67, v67
	v_add_f32_e32 v70, v70, v74
	v_add_f32_e32 v71, v71, v75
	v_add_f32_e32 v66, 1.0, v66
	v_add_f32_e32 v67, 1.0, v67
	v_rcp_f32_e32 v66, v66
	v_rcp_f32_e32 v67, v67
	v_add_f32_e32 v68, v68, v80
	v_add_f32_e32 v69, v69, v81
	v_mul_f32_e32 v68, 0xbfb8aa3b, v68
	v_pk_mul_f32 v[66:67], v[66:67], v[134:135]
	v_mul_f32_e32 v69, 0xbfb8aa3b, v69
	v_add_f32_e32 v74, v66, v66
	v_add_f32_e32 v75, v67, v67
	v_mul_f32_e32 v74, 0x3fb8aa3b, v74
	v_mul_f32_e32 v75, 0x3fb8aa3b, v75
	v_mul_f32_e32 v70, 0xbfb8aa3b, v70
	v_mul_f32_e32 v71, 0xbfb8aa3b, v71
	v_exp_f32_e32 v74, v74
	v_exp_f32_e32 v75, v75
	v_exp_f32_e32 v68, v68
	v_exp_f32_e32 v69, v69
	v_exp_f32_e32 v70, v70
	v_exp_f32_e32 v71, v71
	v_sub_f32_e32 v74, 1.0, v74
	v_sub_f32_e32 v75, 1.0, v75
	v_add_f32_e32 v68, 1.0, v68
	v_add_f32_e32 v69, 1.0, v69
	v_add_f32_e32 v70, 1.0, v70
	v_add_f32_e32 v71, 1.0, v71
	v_max_f32_e32 v74, 0, v74
	v_max_f32_e32 v75, 0, v75
	v_rcp_f32_e32 v68, v68
	v_rcp_f32_e32 v69, v69
	v_rcp_f32_e32 v70, v70
	s_nop 0
	v_mov_b32_e32 v158, v176
	v_mov_b32_e32 v159, v177
	v_lshlrev_b32_e32 v162, 16, v158
	v_and_b32_e32 v163, 0xffff0000, v158
	v_pk_mul_f32 v[126:127], v[122:123], v[162:163]
	v_add_f32_e32 v123, v128, v76
	v_mul_f32_e32 v123, 0xbfb8aa3b, v123
	v_exp_f32_e32 v123, v123
	v_add_f32_e32 v122, v124, v80
	v_mul_f32_e32 v122, 0xbfb8aa3b, v122
	v_exp_f32_e32 v122, v122
	v_add_f32_e32 v123, 1.0, v123
	v_rcp_f32_e32 v124, v123
	v_add_f32_e32 v123, v125, v81
	v_mul_f32_e32 v123, 0xbfb8aa3b, v123
	v_exp_f32_e32 v123, v123
	v_add_f32_e32 v122, 1.0, v122
	v_rcp_f32_e32 v122, v122
	v_add_f32_e32 v125, v129, v77
	v_add_f32_e32 v123, 1.0, v123
	v_rcp_f32_e32 v123, v123
	v_mul_f32_e32 v125, 0xbfb8aa3b, v125
	v_exp_f32_e32 v125, v125
	v_lshlrev_b32_e32 v158, 16, v159
	v_pk_mul_f32 v[128:129], v[122:123], v[132:133]
	v_and_b32_e32 v159, 0xffff0000, v159
	v_add_f32_e32 v122, v128, v128
	v_add_f32_e32 v123, v129, v129
	v_mul_f32_e32 v122, 0x3fb8aa3b, v122
	v_mul_f32_e32 v123, 0x3fb8aa3b, v123
	v_exp_f32_e32 v122, v122
	v_exp_f32_e32 v123, v123
	v_add_f32_e32 v125, 1.0, v125
	v_rcp_f32_e32 v125, v125
	v_sub_f32_e32 v122, 1.0, v122
	v_sub_f32_e32 v123, 1.0, v123
	v_max_f32_e32 v122, 0, v122
	v_max_f32_e32 v123, 0, v123
	v_sqrt_f32_e32 v122, v122
	v_sqrt_f32_e32 v123, v123
	v_cvt_pk_bf16_f32 v126, v126, v127
	v_rcp_f32_e32 v71, v71
	v_sqrt_f32_e32 v74, v74
	v_pk_mul_f32 v[122:123], v[124:125], v[122:123]
	v_sqrt_f32_e32 v75, v75
	v_pk_mul_f32 v[124:125], v[122:123], v[158:159]
	v_cvt_pk_bf16_f32 v159, v128, v129
	v_mad_i64_i32 v[128:129], s[6:7], v136, s84, v[130:131]
	v_lshl_add_u64 v[128:129], v[128:129], 0, v[146:147]
	v_add_co_u32_e32 v128, vcc, s69, v128
	v_add_u32_e32 v122, 16, v136
	v_cvt_pk_bf16_f32 v158, v160, v161
	v_addc_co_u32_e32 v129, vcc, 0, v129, vcc
	v_cvt_pk_bf16_f32 v127, v124, v125
	v_mov_b32_e32 v160, v158
	v_mov_b32_e32 v161, v159
	v_mov_b32_e32 v164, v126
	v_mov_b32_e32 v165, v127
	v_pk_mul_f32 v[126:127], v[114:115], v[134:135]
	v_ashrrev_i32_e32 v123, 31, v122
	v_lshlrev_b64 v[124:125], 11, v[122:123]
	v_lshl_add_u64 v[124:125], s[14:15], 0, v[124:125]
	v_lshl_add_u64 v[124:125], v[124:125], 0, v[146:147]
	s_nop 0
	v_add_f32_e32 v114, v126, v126
	v_add_f32_e32 v115, v127, v127
	v_mul_f32_e32 v114, 0x3fb8aa3b, v114
	v_mul_f32_e32 v115, 0x3fb8aa3b, v115
	v_exp_f32_e32 v114, v114
	v_exp_f32_e32 v115, v115
	v_pk_mul_f32 v[68:69], v[68:69], v[132:133]
	v_pk_mul_f32 v[70:71], v[70:71], v[74:75]
	v_sub_f32_e32 v114, 1.0, v114
	v_sub_f32_e32 v115, 1.0, v115
	v_max_f32_e32 v114, 0, v114
	v_max_f32_e32 v115, 0, v115
	v_sqrt_f32_e32 v114, v114
	v_sqrt_f32_e32 v115, v115
	v_add_f32_e32 v74, v68, v68
	v_add_f32_e32 v75, v69, v69
	v_add_f32_e32 v72, v72, v76
	v_pk_mul_f32 v[114:115], v[118:119], v[114:115]
	v_add_f32_e32 v73, v73, v77
	v_mul_f32_e32 v74, 0x3fb8aa3b, v74
	v_mul_f32_e32 v75, 0x3fb8aa3b, v75
	v_mul_f32_e32 v72, 0xbfb8aa3b, v72
	v_mul_f32_e32 v73, 0xbfb8aa3b, v73
	v_exp_f32_e32 v74, v74
	v_exp_f32_e32 v75, v75
	v_exp_f32_e32 v72, v72
	v_exp_f32_e32 v73, v73
	v_sub_f32_e32 v74, 1.0, v74
	v_sub_f32_e32 v75, 1.0, v75
	v_add_f32_e32 v72, 1.0, v72
	v_add_f32_e32 v73, 1.0, v73
	v_max_f32_e32 v74, 0, v74
	v_max_f32_e32 v75, 0, v75
	v_rcp_f32_e32 v72, v72
	v_rcp_f32_e32 v73, v73
	v_sqrt_f32_e32 v74, v74
	v_sqrt_f32_e32 v75, v75
	v_cvt_pk_bf16_f32 v66, v66, v67
	v_cvt_pk_bf16_f32 v67, v68, v69
	v_pk_mul_f32 v[72:73], v[72:73], v[74:75]
	v_or_b32_e32 v74, 4, v150
	v_ashrrev_i32_e32 v75, 31, v74
	s_nop 0
	v_mov_b32_e32 v124, v190
	v_mov_b32_e32 v125, v191
	v_lshlrev_b32_e32 v128, 16, v124
	v_and_b32_e32 v129, 0xffff0000, v124
	v_pk_mul_f32 v[118:119], v[114:115], v[128:129]
	v_add_f32_e32 v115, v120, v76
	v_mul_f32_e32 v115, 0xbfb8aa3b, v115
	v_exp_f32_e32 v115, v115
	v_add_f32_e32 v114, v116, v80
	v_mul_f32_e32 v114, 0xbfb8aa3b, v114
	v_exp_f32_e32 v114, v114
	v_add_f32_e32 v115, 1.0, v115
	v_rcp_f32_e32 v116, v115
	v_add_f32_e32 v115, v117, v81
	v_mul_f32_e32 v115, 0xbfb8aa3b, v115
	v_exp_f32_e32 v115, v115
	v_add_f32_e32 v114, 1.0, v114
	v_rcp_f32_e32 v114, v114
	v_add_f32_e32 v117, v121, v77
	v_add_f32_e32 v115, 1.0, v115
	v_rcp_f32_e32 v115, v115
	v_mul_f32_e32 v117, 0xbfb8aa3b, v117
	v_exp_f32_e32 v117, v117
	v_lshlrev_b32_e32 v124, 16, v125
	v_pk_mul_f32 v[120:121], v[114:115], v[132:133]
	v_and_b32_e32 v125, 0xffff0000, v125
	v_add_f32_e32 v114, v120, v120
	v_add_f32_e32 v115, v121, v121
	v_mul_f32_e32 v114, 0x3fb8aa3b, v114
	v_mul_f32_e32 v115, 0x3fb8aa3b, v115
	v_exp_f32_e32 v114, v114
	v_exp_f32_e32 v115, v115
	v_add_f32_e32 v117, 1.0, v117
	v_rcp_f32_e32 v117, v117
	v_sub_f32_e32 v114, 1.0, v114
	v_sub_f32_e32 v115, 1.0, v115
	v_max_f32_e32 v114, 0, v114
	v_max_f32_e32 v115, 0, v115
	v_sqrt_f32_e32 v114, v114
	v_sqrt_f32_e32 v115, v115
	v_cvt_pk_bf16_f32 v118, v118, v119
	v_pk_mul_f32 v[114:115], v[116:117], v[114:115]
	s_nop 0
	v_pk_mul_f32 v[116:117], v[114:115], v[124:125]
	v_cvt_pk_bf16_f32 v125, v120, v121
	v_mad_i64_i32 v[120:121], s[6:7], v122, s84, v[130:131]
	v_lshl_add_u64 v[120:121], v[120:121], 0, v[146:147]
	v_add_co_u32_e32 v120, vcc, s69, v120
	v_add_u32_e32 v114, 16, v122
	v_cvt_pk_bf16_f32 v124, v126, v127
	v_addc_co_u32_e32 v121, vcc, 0, v121, vcc
	v_cvt_pk_bf16_f32 v119, v116, v117
	v_mov_b32_e32 v188, v124
	v_mov_b32_e32 v189, v125
	v_mov_b32_e32 v228, v118
	v_mov_b32_e32 v229, v119
	v_pk_mul_f32 v[118:119], v[106:107], v[134:135]
	v_ashrrev_i32_e32 v115, 31, v114
	v_lshlrev_b64 v[116:117], 11, v[114:115]
	v_lshl_add_u64 v[116:117], s[14:15], 0, v[116:117]
	v_lshl_add_u64 v[116:117], v[116:117], 0, v[146:147]
	s_nop 0
	v_add_f32_e32 v106, v118, v118
	v_add_f32_e32 v107, v119, v119
	v_mul_f32_e32 v106, 0x3fb8aa3b, v106
	v_mul_f32_e32 v107, 0x3fb8aa3b, v107
	v_exp_f32_e32 v106, v106
	v_exp_f32_e32 v107, v107
	v_sub_f32_e32 v106, 1.0, v106
	v_sub_f32_e32 v107, 1.0, v107
	v_max_f32_e32 v106, 0, v106
	v_max_f32_e32 v107, 0, v107
	v_sqrt_f32_e32 v106, v106
	v_sqrt_f32_e32 v107, v107
	s_nop 0
	v_mov_b32_e32 v116, v192
	v_mov_b32_e32 v117, v193
	v_lshlrev_b32_e32 v120, 16, v116
	v_and_b32_e32 v121, 0xffff0000, v116
	v_pk_mul_f32 v[106:107], v[110:111], v[106:107]
	v_lshlrev_b32_e32 v116, 16, v117
	v_pk_mul_f32 v[110:111], v[106:107], v[120:121]
	v_add_f32_e32 v107, v112, v76
	v_mul_f32_e32 v107, 0xbfb8aa3b, v107
	v_exp_f32_e32 v107, v107
	v_add_f32_e32 v106, v108, v80
	v_mul_f32_e32 v106, 0xbfb8aa3b, v106
	v_exp_f32_e32 v106, v106
	v_add_f32_e32 v107, 1.0, v107
	v_rcp_f32_e32 v108, v107
	v_add_f32_e32 v107, v109, v81
	v_mul_f32_e32 v107, 0xbfb8aa3b, v107
	v_exp_f32_e32 v107, v107
	v_add_f32_e32 v106, 1.0, v106
	v_rcp_f32_e32 v106, v106
	v_add_f32_e32 v109, v113, v77
	v_add_f32_e32 v107, 1.0, v107
	v_rcp_f32_e32 v107, v107
	v_mul_f32_e32 v109, 0xbfb8aa3b, v109
	v_exp_f32_e32 v109, v109
	v_and_b32_e32 v117, 0xffff0000, v117
	v_pk_mul_f32 v[112:113], v[106:107], v[132:133]
	v_cvt_pk_bf16_f32 v110, v110, v111
	v_add_f32_e32 v106, v112, v112
	v_add_f32_e32 v107, v113, v113
	v_mul_f32_e32 v106, 0x3fb8aa3b, v106
	v_mul_f32_e32 v107, 0x3fb8aa3b, v107
	v_exp_f32_e32 v106, v106
	v_exp_f32_e32 v107, v107
	v_add_f32_e32 v109, 1.0, v109
	v_rcp_f32_e32 v109, v109
	v_sub_f32_e32 v106, 1.0, v106
	v_sub_f32_e32 v107, 1.0, v107
	v_max_f32_e32 v106, 0, v106
	v_max_f32_e32 v107, 0, v107
	v_sqrt_f32_e32 v106, v106
	v_sqrt_f32_e32 v107, v107
	s_nop 0
	v_pk_mul_f32 v[106:107], v[108:109], v[106:107]
	s_nop 0
	v_pk_mul_f32 v[108:109], v[106:107], v[116:117]
	v_cvt_pk_bf16_f32 v117, v112, v113
	v_mad_i64_i32 v[112:113], s[6:7], v114, s84, v[130:131]
	v_lshl_add_u64 v[112:113], v[112:113], 0, v[146:147]
	v_add_co_u32_e32 v112, vcc, s69, v112
	v_add_u32_e32 v106, 0x50, v114
	v_cvt_pk_bf16_f32 v116, v118, v119
	v_addc_co_u32_e32 v113, vcc, 0, v113, vcc
	v_cvt_pk_bf16_f32 v111, v108, v109
	v_mov_b32_e32 v120, v116
	v_mov_b32_e32 v121, v117
	v_mov_b32_e32 v124, v110
	v_mov_b32_e32 v125, v111
	v_pk_mul_f32 v[110:111], v[98:99], v[134:135]
	v_ashrrev_i32_e32 v107, 31, v106
	v_lshlrev_b64 v[108:109], 11, v[106:107]
	v_lshl_add_u64 v[108:109], s[14:15], 0, v[108:109]
	v_lshl_add_u64 v[108:109], v[108:109], 0, v[146:147]
	s_nop 0
	v_add_f32_e32 v98, v110, v110
	v_add_f32_e32 v99, v111, v111
	v_mul_f32_e32 v98, 0x3fb8aa3b, v98
	v_mul_f32_e32 v99, 0x3fb8aa3b, v99
	v_exp_f32_e32 v98, v98
	v_exp_f32_e32 v99, v99
	v_sub_f32_e32 v98, 1.0, v98
	v_sub_f32_e32 v99, 1.0, v99
	v_max_f32_e32 v98, 0, v98
	v_max_f32_e32 v99, 0, v99
	v_sqrt_f32_e32 v98, v98
	v_sqrt_f32_e32 v99, v99
	s_nop 0
	v_mov_b32_e32 v108, v194
	v_mov_b32_e32 v109, v195
	v_lshlrev_b32_e32 v112, 16, v108
	v_and_b32_e32 v113, 0xffff0000, v108
	v_pk_mul_f32 v[98:99], v[102:103], v[98:99]
	v_lshlrev_b32_e32 v108, 16, v109
	v_pk_mul_f32 v[102:103], v[98:99], v[112:113]
	v_add_f32_e32 v99, v104, v76
	v_mul_f32_e32 v99, 0xbfb8aa3b, v99
	v_exp_f32_e32 v99, v99
	v_add_f32_e32 v98, v100, v80
	v_mul_f32_e32 v98, 0xbfb8aa3b, v98
	v_exp_f32_e32 v98, v98
	v_add_f32_e32 v99, 1.0, v99
	v_rcp_f32_e32 v100, v99
	v_add_f32_e32 v99, v101, v81
	v_mul_f32_e32 v99, 0xbfb8aa3b, v99
	v_exp_f32_e32 v99, v99
	v_add_f32_e32 v98, 1.0, v98
	v_rcp_f32_e32 v98, v98
	v_add_f32_e32 v101, v105, v77
	v_add_f32_e32 v99, 1.0, v99
	v_rcp_f32_e32 v99, v99
	v_mul_f32_e32 v101, 0xbfb8aa3b, v101
	v_exp_f32_e32 v101, v101
	v_and_b32_e32 v109, 0xffff0000, v109
	v_pk_mul_f32 v[104:105], v[98:99], v[132:133]
	v_cvt_pk_bf16_f32 v102, v102, v103
	v_add_f32_e32 v98, v104, v104
	v_add_f32_e32 v99, v105, v105
	v_mul_f32_e32 v98, 0x3fb8aa3b, v98
	v_mul_f32_e32 v99, 0x3fb8aa3b, v99
	v_exp_f32_e32 v98, v98
	v_exp_f32_e32 v99, v99
	v_add_f32_e32 v101, 1.0, v101
	v_rcp_f32_e32 v101, v101
	v_sub_f32_e32 v98, 1.0, v98
	v_sub_f32_e32 v99, 1.0, v99
	v_max_f32_e32 v98, 0, v98
	v_max_f32_e32 v99, 0, v99
	v_sqrt_f32_e32 v98, v98
	v_sqrt_f32_e32 v99, v99
	s_nop 0
	v_pk_mul_f32 v[98:99], v[100:101], v[98:99]
	s_nop 0
	v_pk_mul_f32 v[100:101], v[98:99], v[108:109]
	v_cvt_pk_bf16_f32 v109, v104, v105
	v_mad_i64_i32 v[104:105], s[6:7], v106, s84, v[130:131]
	v_lshl_add_u64 v[104:105], v[104:105], 0, v[146:147]
	v_add_co_u32_e32 v104, vcc, s69, v104
	v_add_u32_e32 v98, 16, v106
	v_cvt_pk_bf16_f32 v108, v110, v111
	v_addc_co_u32_e32 v105, vcc, 0, v105, vcc
	v_cvt_pk_bf16_f32 v103, v100, v101
	v_mov_b32_e32 v112, v108
	v_mov_b32_e32 v113, v109
	v_mov_b32_e32 v116, v102
	v_mov_b32_e32 v117, v103
	v_pk_mul_f32 v[102:103], v[90:91], v[134:135]
	v_ashrrev_i32_e32 v99, 31, v98
	v_lshlrev_b64 v[100:101], 11, v[98:99]
	v_lshl_add_u64 v[100:101], s[14:15], 0, v[100:101]
	v_lshl_add_u64 v[100:101], v[100:101], 0, v[146:147]
	s_nop 0
	v_add_f32_e32 v90, v102, v102
	v_add_f32_e32 v91, v103, v103
	v_mul_f32_e32 v90, 0x3fb8aa3b, v90
	v_mul_f32_e32 v91, 0x3fb8aa3b, v91
	v_exp_f32_e32 v90, v90
	v_exp_f32_e32 v91, v91
	v_sub_f32_e32 v90, 1.0, v90
	v_sub_f32_e32 v91, 1.0, v91
	v_max_f32_e32 v90, 0, v90
	v_max_f32_e32 v91, 0, v91
	v_sqrt_f32_e32 v90, v90
	v_sqrt_f32_e32 v91, v91
	s_nop 0
	v_mov_b32_e32 v100, v196
	v_mov_b32_e32 v101, v197
	v_lshlrev_b32_e32 v104, 16, v100
	v_and_b32_e32 v105, 0xffff0000, v100
	v_pk_mul_f32 v[90:91], v[94:95], v[90:91]
	v_lshlrev_b32_e32 v100, 16, v101
	v_pk_mul_f32 v[94:95], v[90:91], v[104:105]
	v_add_f32_e32 v91, v96, v76
	v_mul_f32_e32 v91, 0xbfb8aa3b, v91
	v_exp_f32_e32 v91, v91
	v_add_f32_e32 v90, v92, v80
	v_mul_f32_e32 v90, 0xbfb8aa3b, v90
	v_exp_f32_e32 v90, v90
	v_add_f32_e32 v91, 1.0, v91
	v_rcp_f32_e32 v92, v91
	v_add_f32_e32 v91, v93, v81
	v_mul_f32_e32 v91, 0xbfb8aa3b, v91
	v_exp_f32_e32 v91, v91
	v_add_f32_e32 v90, 1.0, v90
	v_rcp_f32_e32 v90, v90
	v_add_f32_e32 v93, v97, v77
	v_add_f32_e32 v91, 1.0, v91
	v_rcp_f32_e32 v91, v91
	v_mul_f32_e32 v93, 0xbfb8aa3b, v93
	v_exp_f32_e32 v93, v93
	v_and_b32_e32 v101, 0xffff0000, v101
	v_pk_mul_f32 v[96:97], v[90:91], v[132:133]
	v_cvt_pk_bf16_f32 v94, v94, v95
	v_add_f32_e32 v90, v96, v96
	v_add_f32_e32 v91, v97, v97
	v_mul_f32_e32 v90, 0x3fb8aa3b, v90
	v_mul_f32_e32 v91, 0x3fb8aa3b, v91
	v_exp_f32_e32 v90, v90
	v_exp_f32_e32 v91, v91
	v_add_f32_e32 v93, 1.0, v93
	v_rcp_f32_e32 v93, v93
	v_sub_f32_e32 v90, 1.0, v90
	v_sub_f32_e32 v91, 1.0, v91
	v_max_f32_e32 v90, 0, v90
	v_max_f32_e32 v91, 0, v91
	v_sqrt_f32_e32 v90, v90
	v_sqrt_f32_e32 v91, v91
	s_nop 0
	v_pk_mul_f32 v[90:91], v[92:93], v[90:91]
	s_nop 0
	v_pk_mul_f32 v[92:93], v[90:91], v[100:101]
	v_cvt_pk_bf16_f32 v101, v96, v97
	v_mad_i64_i32 v[96:97], s[6:7], v98, s84, v[130:131]
	v_lshl_add_u64 v[96:97], v[96:97], 0, v[146:147]
	v_add_co_u32_e32 v96, vcc, s69, v96
	v_add_u32_e32 v90, 16, v98
	v_cvt_pk_bf16_f32 v100, v102, v103
	v_addc_co_u32_e32 v97, vcc, 0, v97, vcc
	v_cvt_pk_bf16_f32 v95, v92, v93
	v_mov_b32_e32 v104, v100
	v_mov_b32_e32 v105, v101
	v_mov_b32_e32 v108, v94
	v_mov_b32_e32 v109, v95
	v_pk_mul_f32 v[94:95], v[82:83], v[134:135]
	v_ashrrev_i32_e32 v91, 31, v90
	v_lshlrev_b64 v[92:93], 11, v[90:91]
	v_lshl_add_u64 v[92:93], s[14:15], 0, v[92:93]
	v_lshl_add_u64 v[92:93], v[92:93], 0, v[146:147]
	s_nop 0
	v_add_f32_e32 v82, v94, v94
	v_add_f32_e32 v83, v95, v95
	v_mul_f32_e32 v82, 0x3fb8aa3b, v82
	v_mul_f32_e32 v83, 0x3fb8aa3b, v83
	v_exp_f32_e32 v82, v82
	v_exp_f32_e32 v83, v83
	v_sub_f32_e32 v82, 1.0, v82
	v_sub_f32_e32 v83, 1.0, v83
	v_max_f32_e32 v82, 0, v82
	v_max_f32_e32 v83, 0, v83
	v_sqrt_f32_e32 v82, v82
	v_sqrt_f32_e32 v83, v83
	s_nop 0
	v_mov_b32_e32 v92, v198
	v_mov_b32_e32 v93, v199
	v_lshlrev_b32_e32 v96, 16, v92
	v_and_b32_e32 v97, 0xffff0000, v92
	v_pk_mul_f32 v[82:83], v[86:87], v[82:83]
	v_lshlrev_b32_e32 v92, 16, v93
	v_pk_mul_f32 v[86:87], v[82:83], v[96:97]
	v_add_f32_e32 v83, v88, v76
	v_mul_f32_e32 v83, 0xbfb8aa3b, v83
	v_exp_f32_e32 v83, v83
	v_add_f32_e32 v82, v84, v80
	v_mul_f32_e32 v82, 0xbfb8aa3b, v82
	v_exp_f32_e32 v82, v82
	v_add_f32_e32 v83, 1.0, v83
	v_rcp_f32_e32 v84, v83
	v_add_f32_e32 v83, v85, v81
	v_mul_f32_e32 v83, 0xbfb8aa3b, v83
	v_exp_f32_e32 v83, v83
	v_add_f32_e32 v82, 1.0, v82
	v_rcp_f32_e32 v82, v82
	v_add_f32_e32 v85, v89, v77
	v_add_f32_e32 v83, 1.0, v83
	v_rcp_f32_e32 v83, v83
	v_mul_f32_e32 v85, 0xbfb8aa3b, v85
	v_exp_f32_e32 v85, v85
	v_and_b32_e32 v93, 0xffff0000, v93
	v_pk_mul_f32 v[88:89], v[82:83], v[132:133]
	v_cvt_pk_bf16_f32 v86, v86, v87
	v_add_f32_e32 v82, v88, v88
	v_add_f32_e32 v83, v89, v89
	v_mul_f32_e32 v82, 0x3fb8aa3b, v82
	v_mul_f32_e32 v83, 0x3fb8aa3b, v83
	v_exp_f32_e32 v82, v82
	v_exp_f32_e32 v83, v83
	v_add_f32_e32 v85, 1.0, v85
	v_rcp_f32_e32 v85, v85
	v_sub_f32_e32 v82, 1.0, v82
	v_sub_f32_e32 v83, 1.0, v83
	v_max_f32_e32 v82, 0, v82
	v_max_f32_e32 v83, 0, v83
	v_sqrt_f32_e32 v82, v82
	v_sqrt_f32_e32 v83, v83
	s_nop 0
	v_pk_mul_f32 v[82:83], v[84:85], v[82:83]
	s_nop 0
	v_pk_mul_f32 v[84:85], v[82:83], v[92:93]
	v_cvt_pk_bf16_f32 v93, v88, v89
	v_mad_i64_i32 v[88:89], s[6:7], v90, s84, v[130:131]
	v_lshl_add_u64 v[88:89], v[88:89], 0, v[146:147]
	v_add_co_u32_e32 v88, vcc, s69, v88
	v_add_u32_e32 v82, 16, v90
	v_cvt_pk_bf16_f32 v92, v94, v95
	v_addc_co_u32_e32 v89, vcc, 0, v89, vcc
	v_cvt_pk_bf16_f32 v87, v84, v85
	v_mov_b32_e32 v96, v92
	v_mov_b32_e32 v97, v93
	v_mov_b32_e32 v100, v86
	v_mov_b32_e32 v101, v87
	s_nop 0
	v_ashrrev_i32_e32 v83, 31, v82
	v_lshlrev_b64 v[84:85], 11, v[82:83]
	v_lshl_add_u64 v[84:85], s[14:15], 0, v[84:85]
	v_lshl_add_u64 v[84:85], v[84:85], 0, v[146:147]
	s_nop 0
	v_mad_i64_i32 v[68:69], s[6:7], v82, s84, v[130:131]
	v_lshl_add_u64 v[68:69], v[68:69], 0, v[146:147]
	v_add_co_u32_e32 v68, vcc, s69, v68
	s_nop 0
	v_mov_b32_e32 v84, v200
	v_mov_b32_e32 v85, v201
	v_lshlrev_b32_e32 v78, 16, v84
	v_and_b32_e32 v79, 0xffff0000, v84
	v_lshlrev_b32_e32 v76, 16, v85
	v_and_b32_e32 v77, 0xffff0000, v85
	v_pk_mul_f32 v[70:71], v[70:71], v[78:79]
	v_pk_mul_f32 v[72:73], v[72:73], v[76:77]
	v_addc_co_u32_e32 v69, vcc, 0, v69, vcc
	v_mov_b32_e32 v88, v66
	v_mov_b32_e32 v89, v67
	v_cvt_pk_bf16_f32 v66, v70, v71
	v_cvt_pk_bf16_f32 v67, v72, v73
	v_mov_b32_e32 v92, v66
	v_mov_b32_e32 v93, v67
	v_mov_b32_e32 v70, v236
	v_mov_b32_e32 v71, v237
	v_mov_b32_e32 v72, v238
	v_mov_b32_e32 v73, v239
	s_nop 0
	v_mov_b32_e32 v66, v246
	v_mov_b32_e32 v67, v247
	v_mov_b32_e32 v68, v248
	v_mov_b32_e32 v69, v249
	v_mov_b32_e32 v76, v250
	v_mov_b32_e32 v77, v251
	v_mov_b32_e32 v78, v252
	v_mov_b32_e32 v79, v253
	s_waitcnt vmcnt(0)
	v_add_f32_e32 v58, v58, v70
	v_ashrrev_i32_e32 v149, 31, v148
	v_max_f32_e64 v80, -v76, -v76
	v_mul_f32_e64 v76, |v76|, s72
	v_exp_f32_e32 v76, v76
	v_mul_f32_e32 v58, 0xbfb8aa3b, v58
	v_exp_f32_e32 v58, v58
	v_max_f32_e32 v80, 0, v80
	v_add_f32_e32 v76, 1.0, v76
	v_cmp_gt_f32_e32 vcc, s71, v76
	v_add_f32_e32 v58, 1.0, v58
	v_rcp_f32_e32 v86, v58
	v_cndmask_b32_e64 v81, 0, 32, vcc
	v_ldexp_f32 v76, v76, v81
	v_log_f32_e32 v76, v76
	v_add_f32_e32 v58, v62, v66
	v_mul_f32_e32 v58, 0xbfb8aa3b, v58
	v_exp_f32_e32 v58, v58
	v_mul_f32_e32 v81, 0x3f317217, v76
	v_fma_f32 v81, v76, s73, -v81
	v_fmac_f32_e32 v81, 0x3377d1cf, v76
	v_fmac_f32_e32 v81, 0x3f317217, v76
	v_cmp_lt_f32_e64 s[6:7], |v76|, s74
	v_add_f32_e32 v58, 1.0, v58
	v_rcp_f32_e32 v62, v58
	v_cndmask_b32_e64 v76, v76, v81, s[6:7]
	v_cndmask_b32_e32 v81, 0, v243, vcc
	v_sub_f32_e32 v82, v76, v81
	v_max_f32_e64 v76, -v77, -v77
	v_max_f32_e32 v81, 0, v76
	v_mul_f32_e64 v76, |v77|, s72
	v_exp_f32_e32 v76, v76
	v_add_f32_e32 v58, v59, v71
	v_mul_f32_e32 v58, 0xbfb8aa3b, v58
	v_exp_f32_e32 v58, v58
	v_add_f32_e32 v76, 1.0, v76
	v_cmp_gt_f32_e32 vcc, s71, v76
	v_add_f32_e32 v60, v60, v72
	v_add_f32_e32 v58, 1.0, v58
	v_cndmask_b32_e64 v77, 0, 32, vcc
	v_ldexp_f32 v76, v76, v77
	v_log_f32_e32 v76, v76
	v_rcp_f32_e32 v87, v58
	v_add_f32_e32 v58, v63, v67
	v_mul_f32_e32 v58, 0xbfb8aa3b, v58
	v_mul_f32_e32 v77, 0x3f317217, v76
	v_fma_f32 v77, v76, s73, -v77
	v_fmac_f32_e32 v77, 0x3377d1cf, v76
	v_fmac_f32_e32 v77, 0x3f317217, v76
	v_cmp_lt_f32_e64 s[6:7], |v76|, s74
	v_exp_f32_e32 v58, v58
	v_mul_f32_e32 v60, 0xbfb8aa3b, v60
	v_cndmask_b32_e64 v76, v76, v77, s[6:7]
	v_cndmask_b32_e32 v77, 0, v243, vcc
	v_sub_f32_e32 v83, v76, v77
	v_mul_f32_e64 v77, |v78|, s72
	v_exp_f32_e32 v77, v77
	v_max_f32_e64 v76, -v78, -v78
	v_add_f32_e32 v58, 1.0, v58
	v_rcp_f32_e32 v63, v58
	v_add_f32_e32 v77, 1.0, v77
	v_cmp_gt_f32_e32 vcc, s71, v77
	v_pk_add_f32 v[58:59], v[80:81], v[82:83]
	v_exp_f32_e32 v60, v60
	v_cndmask_b32_e64 v78, 0, 32, vcc
	v_ldexp_f32 v77, v77, v78
	v_log_f32_e32 v77, v77
	v_pk_mul_f32 v[58:59], v[58:59], s[2:3] op_sel_hi:[1,0]
	v_add_f32_e32 v60, 1.0, v60
	v_pk_mul_f32 v[80:81], v[86:87], v[58:59]
	v_mul_f32_e32 v78, 0x3f317217, v77
	v_fma_f32 v78, v77, s73, -v78
	v_fmac_f32_e32 v78, 0x3377d1cf, v77
	v_fmac_f32_e32 v78, 0x3f317217, v77
	v_cmp_lt_f32_e64 s[6:7], |v77|, s74
	v_add_f32_e32 v82, v80, v80
	v_add_f32_e32 v83, v81, v81
	v_cndmask_b32_e64 v77, v77, v78, s[6:7]
	v_cndmask_b32_e32 v78, 0, v243, vcc
	v_sub_f32_e32 v78, v77, v78
	v_max_f32_e64 v77, -v79, -v79
	v_mul_f32_e64 v79, |v79|, s72
	v_exp_f32_e32 v79, v79
	v_mul_f32_e32 v82, 0x3fb8aa3b, v82
	v_mul_f32_e32 v83, 0x3fb8aa3b, v83
	v_exp_f32_e32 v82, v82
	v_add_f32_e32 v79, 1.0, v79
	v_cmp_gt_f32_e32 vcc, s71, v79
	v_exp_f32_e32 v83, v83
	v_sub_f32_e32 v82, 1.0, v82
	v_cndmask_b32_e64 v84, 0, 32, vcc
	v_ldexp_f32 v79, v79, v84
	v_log_f32_e32 v79, v79
	v_sub_f32_e32 v83, 1.0, v83
	v_max_f32_e32 v82, 0, v82
	v_max_f32_e32 v83, 0, v83
	v_mul_f32_e32 v84, 0x3f317217, v79
	v_fma_f32 v84, v79, s73, -v84
	v_fmac_f32_e32 v84, 0x3377d1cf, v79
	v_fmac_f32_e32 v84, 0x3f317217, v79
	v_cmp_lt_f32_e64 s[6:7], |v79|, s74
	v_sqrt_f32_e32 v82, v82
	v_sqrt_f32_e32 v83, v83
	v_cndmask_b32_e64 v79, v79, v84, s[6:7]
	v_cndmask_b32_e32 v84, 0, v243, vcc
	v_sub_f32_e32 v79, v79, v84
	v_lshlrev_b64 v[84:85], 11, v[148:149]
	v_lshl_add_u64 v[84:85], s[14:15], 0, v[84:85]
	v_lshl_add_u64 v[84:85], v[84:85], 0, v[146:147]
	s_nop 0
	v_pk_mul_f32 v[62:63], v[62:63], v[82:83]
	v_max_f32_e32 v76, 0, v76
	v_max_f32_e32 v77, 0, v77
	v_add_f32_e32 v50, v50, v70
	v_add_f32_e32 v51, v51, v71
	v_mul_f32_e32 v50, 0xbfb8aa3b, v50
	v_mul_f32_e32 v51, 0xbfb8aa3b, v51
	v_exp_f32_e32 v50, v50
	v_exp_f32_e32 v51, v51
	v_add_f32_e32 v54, v54, v66
	v_add_f32_e32 v55, v55, v67
	v_add_f32_e32 v50, 1.0, v50
	v_add_f32_e32 v51, 1.0, v51
	v_rcp_f32_e32 v50, v50
	v_rcp_f32_e32 v51, v51
	v_mul_f32_e32 v54, 0xbfb8aa3b, v54
	v_mul_f32_e32 v55, 0xbfb8aa3b, v55
	v_exp_f32_e32 v54, v54
	v_exp_f32_e32 v55, v55
	v_add_f32_e32 v42, v42, v70
	v_add_f32_e32 v43, v43, v71
	v_add_f32_e32 v54, 1.0, v54
	v_add_f32_e32 v55, 1.0, v55
	v_rcp_f32_e32 v54, v54
	v_rcp_f32_e32 v55, v55
	v_mul_f32_e32 v42, 0xbfb8aa3b, v42
	v_mul_f32_e32 v43, 0xbfb8aa3b, v43
	v_exp_f32_e32 v42, v42
	v_exp_f32_e32 v43, v43
	v_add_f32_e32 v46, v46, v66
	v_add_f32_e32 v47, v47, v67
	v_add_f32_e32 v42, 1.0, v42
	v_add_f32_e32 v43, 1.0, v43
	v_rcp_f32_e32 v42, v42
	v_rcp_f32_e32 v43, v43
	v_mul_f32_e32 v46, 0xbfb8aa3b, v46
	v_mul_f32_e32 v47, 0xbfb8aa3b, v47
	v_exp_f32_e32 v46, v46
	v_exp_f32_e32 v47, v47
	v_add_f32_e32 v34, v34, v70
	v_add_f32_e32 v35, v35, v71
	v_add_f32_e32 v46, 1.0, v46
	v_add_f32_e32 v47, 1.0, v47
	v_rcp_f32_e32 v46, v46
	v_rcp_f32_e32 v47, v47
	v_mul_f32_e32 v34, 0xbfb8aa3b, v34
	v_mul_f32_e32 v35, 0xbfb8aa3b, v35
	v_exp_f32_e32 v34, v34
	v_exp_f32_e32 v35, v35
	v_add_f32_e32 v38, v38, v66
	v_add_f32_e32 v39, v39, v67
	v_add_f32_e32 v34, 1.0, v34
	v_add_f32_e32 v35, 1.0, v35
	v_rcp_f32_e32 v34, v34
	v_rcp_f32_e32 v35, v35
	v_mul_f32_e32 v38, 0xbfb8aa3b, v38
	v_mul_f32_e32 v39, 0xbfb8aa3b, v39
	v_exp_f32_e32 v38, v38
	v_exp_f32_e32 v39, v39
	v_add_f32_e32 v26, v26, v70
	v_add_f32_e32 v27, v27, v71
	v_add_f32_e32 v38, 1.0, v38
	v_add_f32_e32 v39, 1.0, v39
	v_rcp_f32_e32 v38, v38
	v_rcp_f32_e32 v39, v39
	v_mul_f32_e32 v26, 0xbfb8aa3b, v26
	v_mul_f32_e32 v27, 0xbfb8aa3b, v27
	v_exp_f32_e32 v26, v26
	v_exp_f32_e32 v27, v27
	v_add_f32_e32 v30, v30, v66
	v_add_f32_e32 v31, v31, v67
	v_add_f32_e32 v26, 1.0, v26
	v_add_f32_e32 v27, 1.0, v27
	v_rcp_f32_e32 v26, v26
	v_rcp_f32_e32 v27, v27
	v_mul_f32_e32 v30, 0xbfb8aa3b, v30
	v_mul_f32_e32 v31, 0xbfb8aa3b, v31
	v_exp_f32_e32 v30, v30
	v_exp_f32_e32 v31, v31
	s_nop 0
	v_mov_b32_e32 v84, v202
	v_mov_b32_e32 v85, v203
	v_lshlrev_b32_e32 v86, 16, v84
	v_and_b32_e32 v87, 0xffff0000, v84
	v_pk_mul_f32 v[82:83], v[62:63], v[86:87]
	v_rcp_f32_e32 v62, v60
	v_add_f32_e32 v60, v64, v68
	v_mul_f32_e32 v60, 0xbfb8aa3b, v60
	v_exp_f32_e32 v60, v60
	v_add_f32_e32 v30, 1.0, v30
	v_add_f32_e32 v31, 1.0, v31
	v_rcp_f32_e32 v30, v30
	v_add_f32_e32 v60, 1.0, v60
	v_rcp_f32_e32 v64, v60
	v_add_f32_e32 v60, v61, v73
	v_mul_f32_e32 v60, 0xbfb8aa3b, v60
	v_exp_f32_e32 v60, v60
	v_rcp_f32_e32 v31, v31
	v_add_f32_e32 v18, v18, v70
	v_add_f32_e32 v19, v19, v71
	v_add_f32_e32 v60, 1.0, v60
	v_rcp_f32_e32 v63, v60
	v_add_f32_e32 v60, v65, v69
	v_mul_f32_e32 v60, 0xbfb8aa3b, v60
	v_exp_f32_e32 v60, v60
	v_mul_f32_e32 v18, 0xbfb8aa3b, v18
	v_mul_f32_e32 v19, 0xbfb8aa3b, v19
	v_exp_f32_e32 v18, v18
	v_add_f32_e32 v60, 1.0, v60
	v_rcp_f32_e32 v65, v60
	v_pk_add_f32 v[60:61], v[76:77], v[78:79]
	v_lshlrev_b32_e32 v78, 16, v85
	v_pk_mul_f32 v[60:61], v[60:61], s[2:3] op_sel_hi:[1,0]
	v_and_b32_e32 v79, 0xffff0000, v85
	v_pk_mul_f32 v[62:63], v[62:63], v[60:61]
	v_exp_f32_e32 v19, v19
	v_add_f32_e32 v76, v62, v62
	v_add_f32_e32 v77, v63, v63
	v_mul_f32_e32 v76, 0x3fb8aa3b, v76
	v_mul_f32_e32 v77, 0x3fb8aa3b, v77
	v_exp_f32_e32 v76, v76
	v_exp_f32_e32 v77, v77
	v_add_f32_e32 v18, 1.0, v18
	v_add_f32_e32 v19, 1.0, v19
	v_sub_f32_e32 v76, 1.0, v76
	v_sub_f32_e32 v77, 1.0, v77
	v_max_f32_e32 v76, 0, v76
	v_max_f32_e32 v77, 0, v77
	v_sqrt_f32_e32 v76, v76
	v_sqrt_f32_e32 v77, v77
	v_rcp_f32_e32 v18, v18
	v_rcp_f32_e32 v19, v19
	v_add_f32_e32 v22, v22, v66
	v_pk_mul_f32 v[64:65], v[64:65], v[76:77]
	v_add_f32_e32 v23, v23, v67
	v_pk_mul_f32 v[76:77], v[64:65], v[78:79]
	v_cvt_pk_bf16_f32 v78, v80, v81
	v_cvt_pk_bf16_f32 v79, v62, v63
	v_mad_i64_i32 v[80:81], s[6:7], v148, s84, v[130:131]
	v_lshlrev_b64 v[62:63], 1, v[74:75]
	v_lshl_add_u64 v[74:75], v[80:81], 0, v[62:63]
	v_add_co_u32_e32 v74, vcc, s69, v74
	v_add_u32_e32 v64, 16, v148
	s_nop 0
	v_addc_co_u32_e32 v75, vcc, 0, v75, vcc
	v_mov_b32_e32 v222, v78
	v_mov_b32_e32 v223, v79
	global_store_dwordx4 v[74:75], v[220:223], off offset:2040
	v_cvt_pk_bf16_f32 v78, v82, v83
	v_cvt_pk_bf16_f32 v79, v76, v77
	v_mov_b32_e32 v226, v78
	v_mov_b32_e32 v227, v79
	global_store_dwordx4 v[74:75], v[224:227], off offset:-8
	v_pk_mul_f32 v[76:77], v[50:51], v[58:59]
	v_ashrrev_i32_e32 v65, 31, v64
	v_lshlrev_b64 v[74:75], 11, v[64:65]
	v_lshl_add_u64 v[74:75], s[14:15], 0, v[74:75]
	v_lshl_add_u64 v[74:75], v[74:75], 0, v[146:147]
	s_nop 0
	v_add_f32_e32 v50, v76, v76
	v_add_f32_e32 v51, v77, v77
	v_mul_f32_e32 v50, 0x3fb8aa3b, v50
	v_mul_f32_e32 v51, 0x3fb8aa3b, v51
	v_exp_f32_e32 v50, v50
	v_exp_f32_e32 v51, v51
	v_mul_f32_e32 v22, 0xbfb8aa3b, v22
	v_mul_f32_e32 v23, 0xbfb8aa3b, v23
	v_sub_f32_e32 v50, 1.0, v50
	v_sub_f32_e32 v51, 1.0, v51
	v_max_f32_e32 v50, 0, v50
	v_max_f32_e32 v51, 0, v51
	v_sqrt_f32_e32 v50, v50
	v_sqrt_f32_e32 v51, v51
	v_exp_f32_e32 v22, v22
	v_exp_f32_e32 v23, v23
	v_add_f32_e32 v10, v10, v70
	v_pk_mul_f32 v[50:51], v[54:55], v[50:51]
	v_add_f32_e32 v22, 1.0, v22
	v_add_f32_e32 v23, 1.0, v23
	v_rcp_f32_e32 v22, v22
	v_rcp_f32_e32 v23, v23
	v_add_f32_e32 v11, v11, v71
	v_mul_f32_e32 v10, 0xbfb8aa3b, v10
	v_mul_f32_e32 v11, 0xbfb8aa3b, v11
	v_exp_f32_e32 v10, v10
	v_exp_f32_e32 v11, v11
	v_add_f32_e32 v14, v14, v66
	v_add_f32_e32 v15, v15, v67
	v_add_f32_e32 v10, 1.0, v10
	v_add_f32_e32 v11, 1.0, v11
	v_rcp_f32_e32 v10, v10
	v_rcp_f32_e32 v11, v11
	v_mul_f32_e32 v14, 0xbfb8aa3b, v14
	v_mul_f32_e32 v15, 0xbfb8aa3b, v15
	v_exp_f32_e32 v14, v14
	v_exp_f32_e32 v15, v15
	v_add_f32_e32 v2, v2, v70
	v_add_f32_e32 v3, v3, v71
	v_add_f32_e32 v14, 1.0, v14
	v_add_f32_e32 v15, 1.0, v15
	v_rcp_f32_e32 v14, v14
	v_rcp_f32_e32 v15, v15
	v_mul_f32_e32 v2, 0xbfb8aa3b, v2
	v_mul_f32_e32 v3, 0xbfb8aa3b, v3
	v_exp_f32_e32 v2, v2
	v_exp_f32_e32 v3, v3
	v_add_f32_e32 v4, v4, v72
	v_add_f32_e32 v5, v5, v73
	v_add_f32_e32 v2, 1.0, v2
	v_add_f32_e32 v3, 1.0, v3
	v_rcp_f32_e32 v2, v2
	v_rcp_f32_e32 v3, v3
	v_mul_f32_e32 v4, 0xbfb8aa3b, v4
	v_mul_f32_e32 v5, 0xbfb8aa3b, v5
	v_exp_f32_e32 v4, v4
	v_pk_mul_f32 v[2:3], v[2:3], v[58:59]
	v_exp_f32_e32 v5, v5
	v_add_f32_e32 v6, v6, v66
	v_add_f32_e32 v4, 1.0, v4
	v_rcp_f32_e32 v4, v4
	v_add_f32_e32 v5, 1.0, v5
	v_rcp_f32_e32 v5, v5
	v_add_f32_e32 v7, v7, v67
	v_mul_f32_e32 v6, 0xbfb8aa3b, v6
	v_mul_f32_e32 v7, 0xbfb8aa3b, v7
	v_exp_f32_e32 v6, v6
	v_exp_f32_e32 v7, v7
	v_pk_mul_f32 v[4:5], v[4:5], v[60:61]
	v_add_f32_e32 v8, v8, v68
	v_add_f32_e32 v6, 1.0, v6
	v_add_f32_e32 v7, 1.0, v7
	v_rcp_f32_e32 v6, v6
	v_rcp_f32_e32 v7, v7
	v_add_f32_e32 v9, v9, v69
	v_mul_f32_e32 v8, 0xbfb8aa3b, v8
	v_mul_f32_e32 v9, 0xbfb8aa3b, v9
	v_exp_f32_e32 v8, v8
	v_exp_f32_e32 v9, v9
	s_nop 0
	v_mov_b32_e32 v74, v204
	v_mov_b32_e32 v75, v205
	v_lshlrev_b32_e32 v78, 16, v74
	v_and_b32_e32 v79, 0xffff0000, v74
	v_pk_mul_f32 v[54:55], v[50:51], v[78:79]
	v_add_f32_e32 v51, v56, v68
	v_mul_f32_e32 v51, 0xbfb8aa3b, v51
	v_exp_f32_e32 v51, v51
	v_add_f32_e32 v50, v52, v72
	v_mul_f32_e32 v50, 0xbfb8aa3b, v50
	v_exp_f32_e32 v50, v50
	v_add_f32_e32 v51, 1.0, v51
	v_rcp_f32_e32 v52, v51
	v_add_f32_e32 v51, v53, v73
	v_mul_f32_e32 v51, 0xbfb8aa3b, v51
	v_exp_f32_e32 v51, v51
	v_add_f32_e32 v50, 1.0, v50
	v_rcp_f32_e32 v50, v50
	v_add_f32_e32 v53, v57, v69
	v_add_f32_e32 v51, 1.0, v51
	v_rcp_f32_e32 v51, v51
	v_mul_f32_e32 v53, 0xbfb8aa3b, v53
	v_exp_f32_e32 v53, v53
	v_lshlrev_b32_e32 v74, 16, v75
	v_pk_mul_f32 v[56:57], v[50:51], v[60:61]
	v_and_b32_e32 v75, 0xffff0000, v75
	v_add_f32_e32 v50, v56, v56
	v_add_f32_e32 v51, v57, v57
	v_mul_f32_e32 v50, 0x3fb8aa3b, v50
	v_mul_f32_e32 v51, 0x3fb8aa3b, v51
	v_exp_f32_e32 v50, v50
	v_exp_f32_e32 v51, v51
	v_add_f32_e32 v53, 1.0, v53
	v_rcp_f32_e32 v53, v53
	v_sub_f32_e32 v50, 1.0, v50
	v_sub_f32_e32 v51, 1.0, v51
	v_max_f32_e32 v50, 0, v50
	v_max_f32_e32 v51, 0, v51
	v_sqrt_f32_e32 v50, v50
	v_sqrt_f32_e32 v51, v51
	v_cvt_pk_bf16_f32 v54, v54, v55
	v_add_f32_e32 v8, 1.0, v8
	v_add_f32_e32 v9, 1.0, v9
	v_pk_mul_f32 v[50:51], v[52:53], v[50:51]
	v_rcp_f32_e32 v8, v8
	v_pk_mul_f32 v[52:53], v[50:51], v[74:75]
	v_cvt_pk_bf16_f32 v75, v56, v57
	v_mad_i64_i32 v[56:57], s[6:7], v64, s84, v[130:131]
	v_lshl_add_u64 v[56:57], v[56:57], 0, v[62:63]
	v_add_co_u32_e32 v56, vcc, s69, v56
	v_add_u32_e32 v50, 16, v64
	v_cvt_pk_bf16_f32 v74, v76, v77
	v_addc_co_u32_e32 v57, vcc, 0, v57, vcc
	v_cvt_pk_bf16_f32 v55, v52, v53
	v_mov_b32_e32 v162, v74
	v_mov_b32_e32 v163, v75
	global_store_dwordx4 v[56:57], v[160:163], off offset:2040
	v_mov_b32_e32 v166, v54
	v_mov_b32_e32 v167, v55
	global_store_dwordx4 v[56:57], v[164:167], off offset:-8
	v_pk_mul_f32 v[54:55], v[42:43], v[58:59]
	v_ashrrev_i32_e32 v51, 31, v50
	v_lshlrev_b64 v[52:53], 11, v[50:51]
	v_lshl_add_u64 v[52:53], s[14:15], 0, v[52:53]
	v_lshl_add_u64 v[52:53], v[52:53], 0, v[146:147]
	s_nop 0
	v_add_f32_e32 v42, v54, v54
	v_add_f32_e32 v43, v55, v55
	v_mul_f32_e32 v42, 0x3fb8aa3b, v42
	v_mul_f32_e32 v43, 0x3fb8aa3b, v43
	v_exp_f32_e32 v42, v42
	v_exp_f32_e32 v43, v43
	v_rcp_f32_e32 v9, v9
	s_mov_b32 s2, s22
	v_sub_f32_e32 v42, 1.0, v42
	v_sub_f32_e32 v43, 1.0, v43
	v_max_f32_e32 v42, 0, v42
	v_max_f32_e32 v43, 0, v43
	v_sqrt_f32_e32 v42, v42
	v_sqrt_f32_e32 v43, v43
	s_nop 0
	v_mov_b32_e32 v52, v206
	v_mov_b32_e32 v53, v207
	v_lshlrev_b32_e32 v56, 16, v52
	v_and_b32_e32 v57, 0xffff0000, v52
	v_pk_mul_f32 v[42:43], v[46:47], v[42:43]
	v_lshlrev_b32_e32 v52, 16, v53
	v_pk_mul_f32 v[46:47], v[42:43], v[56:57]
	v_add_f32_e32 v43, v48, v68
	v_mul_f32_e32 v43, 0xbfb8aa3b, v43
	v_exp_f32_e32 v43, v43
	v_add_f32_e32 v42, v44, v72
	v_mul_f32_e32 v42, 0xbfb8aa3b, v42
	v_exp_f32_e32 v42, v42
	v_add_f32_e32 v43, 1.0, v43
	v_rcp_f32_e32 v44, v43
	v_add_f32_e32 v43, v45, v73
	v_mul_f32_e32 v43, 0xbfb8aa3b, v43
	v_exp_f32_e32 v43, v43
	v_add_f32_e32 v42, 1.0, v42
	v_rcp_f32_e32 v42, v42
	v_add_f32_e32 v45, v49, v69
	v_add_f32_e32 v43, 1.0, v43
	v_rcp_f32_e32 v43, v43
	v_mul_f32_e32 v45, 0xbfb8aa3b, v45
	v_exp_f32_e32 v45, v45
	v_and_b32_e32 v53, 0xffff0000, v53
	v_pk_mul_f32 v[48:49], v[42:43], v[60:61]
	v_cvt_pk_bf16_f32 v46, v46, v47
	v_add_f32_e32 v42, v48, v48
	v_add_f32_e32 v43, v49, v49
	v_mul_f32_e32 v42, 0x3fb8aa3b, v42
	v_mul_f32_e32 v43, 0x3fb8aa3b, v43
	v_exp_f32_e32 v42, v42
	v_exp_f32_e32 v43, v43
	v_add_f32_e32 v45, 1.0, v45
	v_rcp_f32_e32 v45, v45
	v_sub_f32_e32 v42, 1.0, v42
	v_sub_f32_e32 v43, 1.0, v43
	v_max_f32_e32 v42, 0, v42
	v_max_f32_e32 v43, 0, v43
	v_sqrt_f32_e32 v42, v42
	v_sqrt_f32_e32 v43, v43
	s_nop 0
	v_pk_mul_f32 v[42:43], v[44:45], v[42:43]
	s_nop 0
	v_pk_mul_f32 v[44:45], v[42:43], v[52:53]
	v_cvt_pk_bf16_f32 v53, v48, v49
	v_mad_i64_i32 v[48:49], s[6:7], v50, s84, v[130:131]
	v_lshl_add_u64 v[48:49], v[48:49], 0, v[62:63]
	v_add_co_u32_e32 v48, vcc, s69, v48
	v_add_u32_e32 v42, 16, v50
	v_cvt_pk_bf16_f32 v52, v54, v55
	v_addc_co_u32_e32 v49, vcc, 0, v49, vcc
	v_cvt_pk_bf16_f32 v47, v44, v45
	v_mov_b32_e32 v190, v52
	v_mov_b32_e32 v191, v53
	global_store_dwordx4 v[48:49], v[188:191], off offset:2040
	v_mov_b32_e32 v230, v46
	v_mov_b32_e32 v231, v47
	global_store_dwordx4 v[48:49], v[228:231], off offset:-8
	v_pk_mul_f32 v[46:47], v[34:35], v[58:59]
	v_ashrrev_i32_e32 v43, 31, v42
	v_lshlrev_b64 v[44:45], 11, v[42:43]
	v_lshl_add_u64 v[44:45], s[14:15], 0, v[44:45]
	v_lshl_add_u64 v[44:45], v[44:45], 0, v[146:147]
	s_nop 0
	v_add_f32_e32 v34, v46, v46
	v_add_f32_e32 v35, v47, v47
	v_mul_f32_e32 v34, 0x3fb8aa3b, v34
	v_mul_f32_e32 v35, 0x3fb8aa3b, v35
	v_exp_f32_e32 v34, v34
	v_exp_f32_e32 v35, v35
	v_sub_f32_e32 v34, 1.0, v34
	v_sub_f32_e32 v35, 1.0, v35
	v_max_f32_e32 v34, 0, v34
	v_max_f32_e32 v35, 0, v35
	v_sqrt_f32_e32 v34, v34
	v_sqrt_f32_e32 v35, v35
	s_nop 0
	v_mov_b32_e32 v44, v208
	v_mov_b32_e32 v45, v209
	v_lshlrev_b32_e32 v48, 16, v44
	v_and_b32_e32 v49, 0xffff0000, v44
	v_pk_mul_f32 v[34:35], v[38:39], v[34:35]
	v_lshlrev_b32_e32 v44, 16, v45
	v_pk_mul_f32 v[38:39], v[34:35], v[48:49]
	v_add_f32_e32 v35, v40, v68
	v_mul_f32_e32 v35, 0xbfb8aa3b, v35
	v_exp_f32_e32 v35, v35
	v_add_f32_e32 v34, v36, v72
	v_mul_f32_e32 v34, 0xbfb8aa3b, v34
	v_exp_f32_e32 v34, v34
	v_add_f32_e32 v35, 1.0, v35
	v_rcp_f32_e32 v36, v35
	v_add_f32_e32 v35, v37, v73
	v_mul_f32_e32 v35, 0xbfb8aa3b, v35
	v_exp_f32_e32 v35, v35
	v_add_f32_e32 v34, 1.0, v34
	v_rcp_f32_e32 v34, v34
	v_add_f32_e32 v37, v41, v69
	v_add_f32_e32 v35, 1.0, v35
	v_rcp_f32_e32 v35, v35
	v_mul_f32_e32 v37, 0xbfb8aa3b, v37
	v_exp_f32_e32 v37, v37
	v_and_b32_e32 v45, 0xffff0000, v45
	v_pk_mul_f32 v[40:41], v[34:35], v[60:61]
	v_cvt_pk_bf16_f32 v38, v38, v39
	v_add_f32_e32 v34, v40, v40
	v_add_f32_e32 v35, v41, v41
	v_mul_f32_e32 v34, 0x3fb8aa3b, v34
	v_mul_f32_e32 v35, 0x3fb8aa3b, v35
	v_exp_f32_e32 v34, v34
	v_exp_f32_e32 v35, v35
	v_add_f32_e32 v37, 1.0, v37
	v_rcp_f32_e32 v37, v37
	v_sub_f32_e32 v34, 1.0, v34
	v_sub_f32_e32 v35, 1.0, v35
	v_max_f32_e32 v34, 0, v34
	v_max_f32_e32 v35, 0, v35
	v_sqrt_f32_e32 v34, v34
	v_sqrt_f32_e32 v35, v35
	s_nop 0
	v_pk_mul_f32 v[34:35], v[36:37], v[34:35]
	s_nop 0
	v_pk_mul_f32 v[36:37], v[34:35], v[44:45]
	v_cvt_pk_bf16_f32 v45, v40, v41
	v_mad_i64_i32 v[40:41], s[6:7], v42, s84, v[130:131]
	v_lshl_add_u64 v[40:41], v[40:41], 0, v[62:63]
	v_add_co_u32_e32 v40, vcc, s69, v40
	v_add_u32_e32 v34, 0x50, v42
	v_cvt_pk_bf16_f32 v44, v46, v47
	v_addc_co_u32_e32 v41, vcc, 0, v41, vcc
	v_cvt_pk_bf16_f32 v39, v36, v37
	v_mov_b32_e32 v122, v44
	v_mov_b32_e32 v123, v45
	global_store_dwordx4 v[40:41], v[120:123], off offset:2040
	v_mov_b32_e32 v126, v38
	v_mov_b32_e32 v127, v39
	global_store_dwordx4 v[40:41], v[124:127], off offset:-8
	v_pk_mul_f32 v[38:39], v[26:27], v[58:59]
	v_ashrrev_i32_e32 v35, 31, v34
	v_lshlrev_b64 v[36:37], 11, v[34:35]
	v_lshl_add_u64 v[36:37], s[14:15], 0, v[36:37]
	v_lshl_add_u64 v[36:37], v[36:37], 0, v[146:147]
	s_nop 0
	v_add_f32_e32 v26, v38, v38
	v_add_f32_e32 v27, v39, v39
	v_mul_f32_e32 v26, 0x3fb8aa3b, v26
	v_mul_f32_e32 v27, 0x3fb8aa3b, v27
	v_exp_f32_e32 v26, v26
	v_exp_f32_e32 v27, v27
	v_sub_f32_e32 v26, 1.0, v26
	v_sub_f32_e32 v27, 1.0, v27
	v_max_f32_e32 v26, 0, v26
	v_max_f32_e32 v27, 0, v27
	v_sqrt_f32_e32 v26, v26
	v_sqrt_f32_e32 v27, v27
	s_nop 0
	v_mov_b32_e32 v36, v210
	v_mov_b32_e32 v37, v211
	v_lshlrev_b32_e32 v40, 16, v36
	v_and_b32_e32 v41, 0xffff0000, v36
	v_pk_mul_f32 v[26:27], v[30:31], v[26:27]
	v_lshlrev_b32_e32 v36, 16, v37
	v_pk_mul_f32 v[30:31], v[26:27], v[40:41]
	v_add_f32_e32 v27, v32, v68
	v_mul_f32_e32 v27, 0xbfb8aa3b, v27
	v_exp_f32_e32 v27, v27
	v_add_f32_e32 v26, v28, v72
	v_mul_f32_e32 v26, 0xbfb8aa3b, v26
	v_exp_f32_e32 v26, v26
	v_add_f32_e32 v27, 1.0, v27
	v_rcp_f32_e32 v28, v27
	v_add_f32_e32 v27, v29, v73
	v_mul_f32_e32 v27, 0xbfb8aa3b, v27
	v_exp_f32_e32 v27, v27
	v_add_f32_e32 v26, 1.0, v26
	v_rcp_f32_e32 v26, v26
	v_add_f32_e32 v29, v33, v69
	v_add_f32_e32 v27, 1.0, v27
	v_rcp_f32_e32 v27, v27
	v_mul_f32_e32 v29, 0xbfb8aa3b, v29
	v_exp_f32_e32 v29, v29
	v_and_b32_e32 v37, 0xffff0000, v37
	v_pk_mul_f32 v[32:33], v[26:27], v[60:61]
	v_cvt_pk_bf16_f32 v30, v30, v31
	v_add_f32_e32 v26, v32, v32
	v_add_f32_e32 v27, v33, v33
	v_mul_f32_e32 v26, 0x3fb8aa3b, v26
	v_mul_f32_e32 v27, 0x3fb8aa3b, v27
	v_exp_f32_e32 v26, v26
	v_exp_f32_e32 v27, v27
	v_add_f32_e32 v29, 1.0, v29
	v_rcp_f32_e32 v29, v29
	v_sub_f32_e32 v26, 1.0, v26
	v_sub_f32_e32 v27, 1.0, v27
	v_max_f32_e32 v26, 0, v26
	v_max_f32_e32 v27, 0, v27
	v_sqrt_f32_e32 v26, v26
	v_sqrt_f32_e32 v27, v27
	s_nop 0
	v_pk_mul_f32 v[26:27], v[28:29], v[26:27]
	s_nop 0
	v_pk_mul_f32 v[28:29], v[26:27], v[36:37]
	v_cvt_pk_bf16_f32 v37, v32, v33
	v_mad_i64_i32 v[32:33], s[6:7], v34, s84, v[130:131]
	v_lshl_add_u64 v[32:33], v[32:33], 0, v[62:63]
	v_add_co_u32_e32 v32, vcc, s69, v32
	v_add_u32_e32 v26, 16, v34
	v_cvt_pk_bf16_f32 v36, v38, v39
	v_addc_co_u32_e32 v33, vcc, 0, v33, vcc
	v_cvt_pk_bf16_f32 v31, v28, v29
	v_mov_b32_e32 v114, v36
	v_mov_b32_e32 v115, v37
	global_store_dwordx4 v[32:33], v[112:115], off offset:2040
	v_mov_b32_e32 v118, v30
	v_mov_b32_e32 v119, v31
	global_store_dwordx4 v[32:33], v[116:119], off offset:-8
	v_pk_mul_f32 v[30:31], v[18:19], v[58:59]
	v_ashrrev_i32_e32 v27, 31, v26
	v_lshlrev_b64 v[28:29], 11, v[26:27]
	v_lshl_add_u64 v[28:29], s[14:15], 0, v[28:29]
	v_lshl_add_u64 v[28:29], v[28:29], 0, v[146:147]
	s_nop 0
	v_add_f32_e32 v18, v30, v30
	v_add_f32_e32 v19, v31, v31
	v_mul_f32_e32 v18, 0x3fb8aa3b, v18
	v_mul_f32_e32 v19, 0x3fb8aa3b, v19
	v_exp_f32_e32 v18, v18
	v_exp_f32_e32 v19, v19
	v_sub_f32_e32 v18, 1.0, v18
	v_sub_f32_e32 v19, 1.0, v19
	v_max_f32_e32 v18, 0, v18
	v_max_f32_e32 v19, 0, v19
	v_sqrt_f32_e32 v18, v18
	v_sqrt_f32_e32 v19, v19
	s_nop 0
	v_mov_b32_e32 v28, v212
	v_mov_b32_e32 v29, v213
	v_lshlrev_b32_e32 v32, 16, v28
	v_and_b32_e32 v33, 0xffff0000, v28
	v_pk_mul_f32 v[18:19], v[22:23], v[18:19]
	v_lshlrev_b32_e32 v28, 16, v29
	v_pk_mul_f32 v[22:23], v[18:19], v[32:33]
	v_add_f32_e32 v19, v24, v68
	v_mul_f32_e32 v19, 0xbfb8aa3b, v19
	v_exp_f32_e32 v19, v19
	v_add_f32_e32 v18, v20, v72
	v_mul_f32_e32 v18, 0xbfb8aa3b, v18
	v_exp_f32_e32 v18, v18
	v_add_f32_e32 v19, 1.0, v19
	v_rcp_f32_e32 v20, v19
	v_add_f32_e32 v19, v21, v73
	v_mul_f32_e32 v19, 0xbfb8aa3b, v19
	v_exp_f32_e32 v19, v19
	v_add_f32_e32 v18, 1.0, v18
	v_rcp_f32_e32 v18, v18
	v_add_f32_e32 v21, v25, v69
	v_add_f32_e32 v19, 1.0, v19
	v_rcp_f32_e32 v19, v19
	v_mul_f32_e32 v21, 0xbfb8aa3b, v21
	v_exp_f32_e32 v21, v21
	v_and_b32_e32 v29, 0xffff0000, v29
	v_pk_mul_f32 v[24:25], v[18:19], v[60:61]
	v_cvt_pk_bf16_f32 v22, v22, v23
	v_add_f32_e32 v18, v24, v24
	v_add_f32_e32 v19, v25, v25
	v_mul_f32_e32 v18, 0x3fb8aa3b, v18
	v_mul_f32_e32 v19, 0x3fb8aa3b, v19
	v_exp_f32_e32 v18, v18
	v_exp_f32_e32 v19, v19
	v_add_f32_e32 v21, 1.0, v21
	v_rcp_f32_e32 v21, v21
	v_sub_f32_e32 v18, 1.0, v18
	v_sub_f32_e32 v19, 1.0, v19
	v_max_f32_e32 v18, 0, v18
	v_max_f32_e32 v19, 0, v19
	v_sqrt_f32_e32 v18, v18
	v_sqrt_f32_e32 v19, v19
	s_nop 0
	v_pk_mul_f32 v[18:19], v[20:21], v[18:19]
	s_nop 0
	v_pk_mul_f32 v[20:21], v[18:19], v[28:29]
	v_cvt_pk_bf16_f32 v29, v24, v25
	v_mad_i64_i32 v[24:25], s[6:7], v26, s84, v[130:131]
	v_lshl_add_u64 v[24:25], v[24:25], 0, v[62:63]
	v_add_co_u32_e32 v24, vcc, s69, v24
	v_add_u32_e32 v18, 16, v26
	v_cvt_pk_bf16_f32 v28, v30, v31
	v_addc_co_u32_e32 v25, vcc, 0, v25, vcc
	v_cvt_pk_bf16_f32 v23, v20, v21
	v_mov_b32_e32 v106, v28
	v_mov_b32_e32 v107, v29
	global_store_dwordx4 v[24:25], v[104:107], off offset:2040
	v_mov_b32_e32 v110, v22
	v_mov_b32_e32 v111, v23
	global_store_dwordx4 v[24:25], v[108:111], off offset:-8
	v_pk_mul_f32 v[22:23], v[10:11], v[58:59]
	v_ashrrev_i32_e32 v19, 31, v18
	v_lshlrev_b64 v[20:21], 11, v[18:19]
	v_lshl_add_u64 v[20:21], s[14:15], 0, v[20:21]
	v_lshl_add_u64 v[20:21], v[20:21], 0, v[146:147]
	s_nop 0
	v_add_f32_e32 v10, v22, v22
	v_add_f32_e32 v11, v23, v23
	v_mul_f32_e32 v10, 0x3fb8aa3b, v10
	v_mul_f32_e32 v11, 0x3fb8aa3b, v11
	v_exp_f32_e32 v10, v10
	v_exp_f32_e32 v11, v11
	v_sub_f32_e32 v10, 1.0, v10
	v_sub_f32_e32 v11, 1.0, v11
	v_max_f32_e32 v10, 0, v10
	v_max_f32_e32 v11, 0, v11
	v_sqrt_f32_e32 v10, v10
	v_sqrt_f32_e32 v11, v11
	s_nop 0
	v_mov_b32_e32 v20, v214
	v_mov_b32_e32 v21, v215
	v_lshlrev_b32_e32 v24, 16, v20
	v_and_b32_e32 v25, 0xffff0000, v20
	v_pk_mul_f32 v[10:11], v[14:15], v[10:11]
	v_lshlrev_b32_e32 v20, 16, v21
	v_pk_mul_f32 v[14:15], v[10:11], v[24:25]
	v_add_f32_e32 v11, v16, v68
	v_mul_f32_e32 v11, 0xbfb8aa3b, v11
	v_exp_f32_e32 v11, v11
	v_add_f32_e32 v10, v12, v72
	v_mul_f32_e32 v10, 0xbfb8aa3b, v10
	v_exp_f32_e32 v10, v10
	v_add_f32_e32 v11, 1.0, v11
	v_rcp_f32_e32 v12, v11
	v_add_f32_e32 v11, v13, v73
	v_mul_f32_e32 v11, 0xbfb8aa3b, v11
	v_exp_f32_e32 v11, v11
	v_add_f32_e32 v10, 1.0, v10
	v_rcp_f32_e32 v10, v10
	v_add_f32_e32 v13, v17, v69
	v_add_f32_e32 v11, 1.0, v11
	v_rcp_f32_e32 v11, v11
	v_mul_f32_e32 v13, 0xbfb8aa3b, v13
	v_exp_f32_e32 v13, v13
	v_and_b32_e32 v21, 0xffff0000, v21
	v_pk_mul_f32 v[16:17], v[10:11], v[60:61]
	v_cvt_pk_bf16_f32 v14, v14, v15
	v_add_f32_e32 v10, v16, v16
	v_add_f32_e32 v11, v17, v17
	v_mul_f32_e32 v10, 0x3fb8aa3b, v10
	v_mul_f32_e32 v11, 0x3fb8aa3b, v11
	v_exp_f32_e32 v10, v10
	v_exp_f32_e32 v11, v11
	v_add_f32_e32 v13, 1.0, v13
	v_rcp_f32_e32 v13, v13
	v_sub_f32_e32 v10, 1.0, v10
	v_sub_f32_e32 v11, 1.0, v11
	v_max_f32_e32 v10, 0, v10
	v_max_f32_e32 v11, 0, v11
	v_sqrt_f32_e32 v10, v10
	v_sqrt_f32_e32 v11, v11
	s_nop 0
	v_pk_mul_f32 v[10:11], v[12:13], v[10:11]
	s_nop 0
	v_pk_mul_f32 v[12:13], v[10:11], v[20:21]
	v_cvt_pk_bf16_f32 v21, v16, v17
	v_mad_i64_i32 v[16:17], s[6:7], v18, s84, v[130:131]
	v_lshl_add_u64 v[16:17], v[16:17], 0, v[62:63]
	v_add_co_u32_e32 v16, vcc, s69, v16
	v_add_u32_e32 v10, 16, v18
	v_cvt_pk_bf16_f32 v20, v22, v23
	v_addc_co_u32_e32 v17, vcc, 0, v17, vcc
	v_cvt_pk_bf16_f32 v15, v12, v13
	v_mov_b32_e32 v98, v20
	v_mov_b32_e32 v99, v21
	global_store_dwordx4 v[16:17], v[96:99], off offset:2040
	v_mov_b32_e32 v102, v14
	v_mov_b32_e32 v103, v15
	global_store_dwordx4 v[16:17], v[100:103], off offset:-8
	s_nop 0
	v_ashrrev_i32_e32 v11, 31, v10
	v_lshlrev_b64 v[12:13], 11, v[10:11]
	v_lshl_add_u64 v[12:13], s[14:15], 0, v[12:13]
	v_lshl_add_u64 v[12:13], v[12:13], 0, v[146:147]
	s_nop 0
	v_add_f32_e32 v11, v2, v2
	v_mul_f32_e32 v11, 0x3fb8aa3b, v11
	v_exp_f32_e32 v11, v11
	v_cvt_pk_bf16_f32 v2, v2, v3
	v_sub_f32_e32 v11, 1.0, v11
	v_max_f32_e32 v11, 0, v11
	v_sqrt_f32_e32 v14, v11
	v_add_f32_e32 v11, v3, v3
	v_mul_f32_e32 v11, 0x3fb8aa3b, v11
	v_exp_f32_e32 v11, v11
	v_cvt_pk_bf16_f32 v3, v4, v5
	v_sub_f32_e32 v11, 1.0, v11
	v_max_f32_e32 v11, 0, v11
	v_sqrt_f32_e32 v15, v11
	v_add_f32_e32 v11, v4, v4
	v_mul_f32_e32 v11, 0x3fb8aa3b, v11
	v_exp_f32_e32 v11, v11
	v_pk_mul_f32 v[6:7], v[6:7], v[14:15]
	v_sub_f32_e32 v11, 1.0, v11
	v_max_f32_e32 v11, 0, v11
	v_sqrt_f32_e32 v14, v11
	v_add_f32_e32 v11, v5, v5
	v_mul_f32_e32 v11, 0x3fb8aa3b, v11
	v_exp_f32_e32 v11, v11
	v_mad_i64_i32 v[4:5], s[6:7], v10, s84, v[130:131]
	v_lshl_add_u64 v[4:5], v[4:5], 0, v[62:63]
	v_sub_f32_e32 v11, 1.0, v11
	v_max_f32_e32 v11, 0, v11
	v_sqrt_f32_e32 v15, v11
	v_add_co_u32_e32 v4, vcc, s69, v4
	v_pk_mul_f32 v[8:9], v[8:9], v[14:15]
	s_nop 0
	v_addc_co_u32_e32 v5, vcc, 0, v5, vcc
	v_mov_b32_e32 v90, v2
	v_mov_b32_e32 v91, v3
	global_store_dwordx4 v[4:5], v[88:91], off offset:2040
	s_andn2_b64 vcc, exec, s[4:5]
	s_nop 0
	v_mov_b32_e32 v12, v216
	v_mov_b32_e32 v13, v217
	v_lshlrev_b32_e32 v16, 16, v12
	v_and_b32_e32 v17, 0xffff0000, v12
	v_lshlrev_b32_e32 v12, 16, v13
	v_and_b32_e32 v13, 0xffff0000, v13
	v_pk_mul_f32 v[6:7], v[6:7], v[16:17]
	v_pk_mul_f32 v[8:9], v[8:9], v[12:13]
	v_cvt_pk_bf16_f32 v2, v6, v7
	v_cvt_pk_bf16_f32 v3, v8, v9
	v_mov_b32_e32 v94, v2
	v_mov_b32_e32 v95, v3
	global_store_dwordx4 v[4:5], v[92:95], off offset:-8
	s_cbranch_vccz .LBB0_1214
